# softmax threshold test on per-lane maxima; the cross-half permlane max exchange only on the rare rescale path (8 fewer instructions per tile and wave)
# baseline (speedup 1.0000x reference)
; #define LAS __attribute__((address_space(3)))
; __device__ __forceinline__ void softmax_blk(f32x16& p0, f32x16& p1, f32x16& o0, f32x16& o1, float& mhat, float& lrun, u32x4 (&pf)[4], bool first) {
;     float r0 = max2_(p0[0], p0[1]), r1 = max2_(p1[0], p1[1]);
; #pragma unroll
;     for (int e = 2; e < 16; ++e) { r0 = max2_(r0, p0[e]); r1 = max2_(r1, p1[e]); }
;     const float rm = swap_max(max2_(r0, r1));
;     if (first || __any(rm - mhat > THR)) {
;         const float mn = first ? rm : fmaxf(rm, mhat); const float f = first ? 0.f : __builtin_amdgcn_exp2f(mhat - mn); mhat = mn; lrun *= f;
; #pragma unroll
;         for (int e = 0; e < 16; ++e) { o0[e] *= f; o1[e] *= f; }
;     }
;     float s0 = 0.f, s1 = 0.f;
; #pragma unroll
;     for (int e = 0; e < 16; ++e) { p0[e] = __builtin_amdgcn_exp2f(p0[e] - mhat); p1[e] = __builtin_amdgcn_exp2f(p1[e] - mhat); s0 += p0[e]; s1 += p1[e]; }
;     lrun += s0 + s1;
;     pf[0] = MLA_PACK(p0, 0); pf[1] = MLA_PACK(p0, 8); pf[2] = MLA_PACK(p1, 0); pf[3] = MLA_PACK(p1, 8);
; }
; __device__ __forceinline__ void attn_unit(const bf16_t* Qh, const bf16_t* Kh, const bf16_t* Vh, bf16_t* Oh  , int S, int qb, LAS unsigned char* lds, int tid) {
;     ...
;         {
;             f32x16 p0 = {}, p1 = {};
; #pragma unroll
;             for (int s = 0; s < 6; ++s) {
;                 const bf16x8 a0 = *(const LAS bf16x8*)(lds + cur + kfo + s * 32), a1 = *(const LAS bf16x8*)(lds + cur + kfo + 32 * KPITCH + s * 32);
;                 const bf16x8 q = *(const LAS bf16x8*)(ql + s * 1024);
;                 p0 = __builtin_amdgcn_mfma_f32_32x32x16_bf16(a0, q, p0, 0, 0, 0); p1 = __builtin_amdgcn_mfma_f32_32x32x16_bf16(a1, q, p1, 0, 0, 0);
;             }
;             softmax_blk(p0, p1, oa0, oa1, ma, la, pf, t == 0);
;             pv_blk(pf, oa0, oa1, lds + cur + vb);
;         }
;         __builtin_amdgcn_sched_barrier(0);
;         {
;             f32x16 p0 = {}, p1 = {};
; #pragma unroll
;             for (int s = 0; s < 6; ++s) {
;                 const bf16x8 a0 = *(const LAS bf16x8*)(lds + cur + kfo + s * 32), a1 = *(const LAS bf16x8*)(lds + cur + kfo + 32 * KPITCH + s * 32);
;                 const bf16x8 q = *(const LAS bf16x8*)(ql + (6 + s) * 1024);
;                 p0 = __builtin_amdgcn_mfma_f32_32x32x16_bf16(a0, q, p0, 0, 0, 0); p1 = __builtin_amdgcn_mfma_f32_32x32x16_bf16(a1, q, p1, 0, 0, 0);
;             }
.Lmla_prio:
	s_add_u32 s100, s100, 0x2000
	s_addc_u32 s101, s101, 0
	ds_read_b128 v[128:131], v155
	ds_read_b128 v[142:145], v155 offset:6656
	ds_read_b128 v[162:165], v135 offset:43008
	ds_read_b128 v[176:179], v155 offset:32
	ds_read_b128 v[180:183], v155 offset:6688
	ds_read_b128 v[186:189], v135 offset:44032
	s_waitcnt lgkmcnt(3)
	v_mfma_f32_32x32x16_bf16 v[64:79], v[128:131], v[162:165], 0
	v_mfma_f32_32x32x16_bf16 v[80:95], v[142:145], v[162:165], 0
	ds_read_b128 v[128:131], v155 offset:64
	ds_read_b128 v[142:145], v155 offset:6720
	ds_read_b128 v[162:165], v135 offset:45056
	global_load_dwordx4 v[218:221], v171, s[26:27]
	global_load_dwordx4 v[222:225], v184, s[26:27]
	s_add_u32 s26, s26, 0x3000
	s_addc_u32 s27, s27, 0
	s_waitcnt lgkmcnt(3)
	v_mfma_f32_32x32x16_bf16 v[64:79], v[176:179], v[186:189], v[64:79]
	v_mfma_f32_32x32x16_bf16 v[80:95], v[180:183], v[186:189], v[80:95]
	ds_read_b128 v[176:179], v155 offset:96
	ds_read_b128 v[180:183], v155 offset:6752
	ds_read_b128 v[186:189], v135 offset:46080
	s_waitcnt lgkmcnt(3)
	v_mfma_f32_32x32x16_bf16 v[64:79], v[128:131], v[162:165], v[64:79]
	v_mfma_f32_32x32x16_bf16 v[80:95], v[142:145], v[162:165], v[80:95]
	ds_read_b128 v[128:131], v155 offset:128
	ds_read_b128 v[142:145], v155 offset:6784
	ds_read_b128 v[162:165], v135 offset:47104
	s_waitcnt lgkmcnt(3)
	v_mfma_f32_32x32x16_bf16 v[64:79], v[176:179], v[186:189], v[64:79]
	v_mfma_f32_32x32x16_bf16 v[80:95], v[180:183], v[186:189], v[80:95]
	ds_read_b128 v[176:179], v155 offset:160
	ds_read_b128 v[180:183], v155 offset:6816
	ds_read_b128 v[186:189], v135 offset:48128
	s_waitcnt lgkmcnt(3)
	v_mfma_f32_32x32x16_bf16 v[64:79], v[128:131], v[162:165], v[64:79]
	v_mfma_f32_32x32x16_bf16 v[80:95], v[142:145], v[162:165], v[80:95]
	ds_read_b128 v[128:131], v155
	ds_read_b128 v[142:145], v155 offset:6656
	ds_read_b128 v[162:165], v135 offset:49152
	s_waitcnt lgkmcnt(3)
	v_mfma_f32_32x32x16_bf16 v[64:79], v[176:179], v[186:189], v[64:79]
	v_mfma_f32_32x32x16_bf16 v[80:95], v[180:183], v[186:189], v[80:95]
	ds_read_b128 v[176:179], v155 offset:32
	ds_read_b128 v[180:183], v155 offset:6688
	ds_read_b128 v[186:189], v135 offset:50176
	s_waitcnt lgkmcnt(3)
	v_mfma_f32_32x32x16_bf16 v[96:111], v[128:131], v[162:165], 0
	v_mfma_f32_32x32x16_bf16 v[112:127], v[142:145], v[162:165], 0
	ds_read_b128 v[128:131], v155 offset:64
	ds_read_b128 v[142:145], v155 offset:6720
	ds_read_b128 v[162:165], v135 offset:51200
	s_nop 5
	v_max3_f32 v248, v64, v65, v66
	v_max3_f32 v249, v80, v81, v82
	v_max3_f32 v248, v248, v67, v68
	v_max3_f32 v249, v249, v83, v84
	v_max3_f32 v248, v248, v69, v70
	v_max3_f32 v249, v249, v85, v86
	v_max3_f32 v248, v248, v71, v72
	v_max3_f32 v249, v249, v87, v88
	v_max3_f32 v248, v248, v73, v74
	v_max3_f32 v249, v249, v89, v90
	v_max3_f32 v248, v248, v75, v76
	v_max3_f32 v249, v249, v91, v92
	v_max3_f32 v248, v248, v77, v78
	v_max3_f32 v249, v249, v93, v94
	v_max3_f32 v248, v248, v79, v95
	v_max_f32_e32 v248, v248, v249
	v_mov_b32_e32 v251, v248
	s_nop 1
	v_permlane32_swap_b32_e32 v248, v251
	v_max_f32_e32 v167, v248, v251
	v_sub_f32_e32 v64, v64, v167
	v_sub_f32_e32 v65, v65, v167
	v_sub_f32_e32 v66, v66, v167
	v_sub_f32_e32 v67, v67, v167
	v_sub_f32_e32 v68, v68, v167
	v_sub_f32_e32 v69, v69, v167
	v_sub_f32_e32 v70, v70, v167
	v_sub_f32_e32 v71, v71, v167
	s_waitcnt lgkmcnt(3)
	v_mfma_f32_32x32x16_bf16 v[96:111], v[176:179], v[186:189], v[96:111]
	v_mfma_f32_32x32x16_bf16 v[112:127], v[180:183], v[186:189], v[112:127]
	ds_read_b128 v[176:179], v155 offset:96
	ds_read_b128 v[180:183], v155 offset:6752
	ds_read_b128 v[186:189], v135 offset:52224
	v_sub_f32_e32 v72, v72, v167
	v_sub_f32_e32 v73, v73, v167
	v_sub_f32_e32 v74, v74, v167
	v_sub_f32_e32 v75, v75, v167
	v_sub_f32_e32 v76, v76, v167
	v_sub_f32_e32 v77, v77, v167
	v_sub_f32_e32 v78, v78, v167
	v_sub_f32_e32 v79, v79, v167
	v_sub_f32_e32 v80, v80, v167
	v_sub_f32_e32 v81, v81, v167
	v_sub_f32_e32 v82, v82, v167
	v_sub_f32_e32 v83, v83, v167
	v_sub_f32_e32 v84, v84, v167
	v_sub_f32_e32 v85, v85, v167
	v_sub_f32_e32 v86, v86, v167
	v_sub_f32_e32 v87, v87, v167
	v_sub_f32_e32 v88, v88, v167
	v_sub_f32_e32 v89, v89, v167
	v_sub_f32_e32 v90, v90, v167
	v_sub_f32_e32 v91, v91, v167
	v_sub_f32_e32 v92, v92, v167
	v_sub_f32_e32 v93, v93, v167
	v_sub_f32_e32 v94, v94, v167
	v_sub_f32_e32 v95, v95, v167
	v_sub_f32_e32 v232, 0, v167
	v_sub_f32_e32 v233, 0, v167
	v_sub_f32_e32 v234, 0, v167
	v_sub_f32_e32 v235, 0, v167
	s_waitcnt lgkmcnt(3)
	v_mfma_f32_32x32x16_bf16 v[96:111], v[128:131], v[162:165], v[96:111]
	v_mfma_f32_32x32x16_bf16 v[112:127], v[142:145], v[162:165], v[112:127]
	ds_read_b128 v[128:131], v155 offset:128
	ds_read_b128 v[142:145], v155 offset:6784
	ds_read_b128 v[162:165], v135 offset:53248
	v_sub_f32_e32 v236, 0, v167
	v_sub_f32_e32 v237, 0, v167
	v_sub_f32_e32 v238, 0, v167
	v_sub_f32_e32 v239, 0, v167
	v_sub_f32_e32 v240, 0, v167
	v_sub_f32_e32 v241, 0, v167
	v_sub_f32_e32 v242, 0, v167
	v_sub_f32_e32 v243, 0, v167
	v_sub_f32_e32 v244, 0, v167
	v_sub_f32_e32 v245, 0, v167
	v_sub_f32_e32 v246, 0, v167
	v_sub_f32_e32 v247, 0, v167
	v_max3_f32 v248, v64, v65, v66
	v_max3_f32 v249, v80, v81, v82
	v_max3_f32 v248, v248, v67, v68
	v_max3_f32 v249, v249, v83, v84
	v_max3_f32 v248, v248, v69, v70
	v_max3_f32 v249, v249, v85, v86
	v_max3_f32 v248, v248, v71, v72
	v_max3_f32 v249, v249, v87, v88
	v_max3_f32 v248, v248, v73, v74
	v_max3_f32 v249, v249, v89, v90
	v_max3_f32 v248, v248, v75, v76
	v_max3_f32 v249, v249, v91, v92
	v_max3_f32 v248, v248, v77, v78
	v_max3_f32 v249, v249, v93, v94
	v_max3_f32 v248, v248, v79, v95
	s_waitcnt lgkmcnt(3)
	v_mfma_f32_32x32x16_bf16 v[96:111], v[176:179], v[186:189], v[96:111]
	v_mfma_f32_32x32x16_bf16 v[112:127], v[180:183], v[186:189], v[112:127]
	ds_read_b128 v[176:179], v155 offset:160
	ds_read_b128 v[180:183], v155 offset:6816
	ds_read_b128 v[186:189], v135 offset:54272
	v_max_f32_e32 v248, v248, v249
	v_cmp_lt_f32_e32 vcc, s72, v248
	s_cbranch_vccnz .Lmla_rescAp
; #define LAS __attribute__((address_space(3)))
; __device__ __forceinline__ float swap_max(float m) { auto rr = __builtin_amdgcn_permlane32_swap(__float_as_uint(m), __float_as_uint(m), false, false); return fmaxf(__uint_as_float(rr[0]), __uint_as_float(rr[1])); }
; #define MLA_PACK(P, b) (u32x4){cvt_pk_bf16(P[b], P[b + 1]), cvt_pk_bf16(P[b + 2], P[b + 3]), cvt_pk_bf16(P[b + 4], P[b + 5]), cvt_pk_bf16(P[b + 6], P[b + 7])}
; __device__ __forceinline__ void softmax_blk(f32x16& p0, f32x16& p1, f32x16& o0, f32x16& o1, float& mhat, float& lrun, u32x4 (&pf)[4], bool first) {
;     float r0 = max2_(p0[0], p0[1]), r1 = max2_(p1[0], p1[1]);
; #pragma unroll
;     for (int e = 2; e < 16; ++e) { r0 = max2_(r0, p0[e]); r1 = max2_(r1, p1[e]); }
;     const float rm = swap_max(max2_(r0, r1));
;     if (first || __any(rm - mhat > THR)) {
;         const float mn = first ? rm : fmaxf(rm, mhat); const float f = first ? 0.f : __builtin_amdgcn_exp2f(mhat - mn); mhat = mn; lrun *= f;
; #pragma unroll
;         for (int e = 0; e < 16; ++e) { o0[e] *= f; o1[e] *= f; }
;     }
;     float s0 = 0.f, s1 = 0.f;
; #pragma unroll
;     for (int e = 0; e < 16; ++e) { p0[e] = __builtin_amdgcn_exp2f(p0[e] - mhat); p1[e] = __builtin_amdgcn_exp2f(p1[e] - mhat); s0 += p0[e]; s1 += p1[e]; }
;     lrun += s0 + s1;
;     pf[0] = MLA_PACK(p0, 0); pf[1] = MLA_PACK(p0, 8); pf[2] = MLA_PACK(p1, 0); pf[3] = MLA_PACK(p1, 8);
; }
; __device__ __forceinline__ void attn_unit(const bf16_t* Qh, const bf16_t* Kh, const bf16_t* Vh, bf16_t* Oh  , int S, int qb, LAS unsigned char* lds, int tid) {
;     ...
;         {
;             f32x16 p0 = {}, p1 = {};
; #pragma unroll
;             for (int s = 0; s < 6; ++s) {
;                 const bf16x8 a0 = *(const LAS bf16x8*)(lds + cur + kfo + s * 32), a1 = *(const LAS bf16x8*)(lds + cur + kfo + 32 * KPITCH + s * 32);
;                 const bf16x8 q = *(const LAS bf16x8*)(ql + (6 + s) * 1024);
;                 p0 = __builtin_amdgcn_mfma_f32_32x32x16_bf16(a0, q, p0, 0, 0, 0); p1 = __builtin_amdgcn_mfma_f32_32x32x16_bf16(a1, q, p1, 0, 0, 0);
;             }
;             softmax_blk(p0, p1, ob0, ob1, mb, lb, pf, t == 0);
;             pv_blk(pf, ob0, ob1, lds + cur + vb);
;         }
;         *(LAS u32x4*)(lds + nxt + kd0) = ka; *(LAS u32x4*)(lds + (has1 ? nxt : 0u) + kd1) = kb; *(LAS u32x4*)(lds + nxt + vd) = va;
;         __syncthreads();
.Lmla_rescAp_back:
	v_exp_f32_e32 v64, v64
	v_exp_f32_e32 v65, v65
	v_exp_f32_e32 v66, v66
	v_exp_f32_e32 v67, v67
	v_exp_f32_e32 v68, v68
	v_exp_f32_e32 v69, v69
	v_exp_f32_e32 v70, v70
	v_exp_f32_e32 v71, v71
	v_add_f32_e32 v166, v64, v65
	v_add_f32_e32 v140, v140, v66
	v_add_f32_e32 v166, v166, v67
	v_cvt_pk_bf16_f32 v64, v64, v65
	v_cvt_pk_bf16_f32 v65, v66, v67
	v_exp_f32_e32 v72, v72
	v_exp_f32_e32 v73, v73
	v_exp_f32_e32 v74, v74
	v_exp_f32_e32 v75, v75
	v_add_f32_e32 v140, v140, v68
	v_add_f32_e32 v166, v166, v69
	v_add_f32_e32 v140, v140, v70
	v_add_f32_e32 v166, v166, v71
	v_cvt_pk_bf16_f32 v66, v68, v69
	v_cvt_pk_bf16_f32 v67, v70, v71
	v_exp_f32_e32 v76, v76
	v_exp_f32_e32 v77, v77
	s_waitcnt lgkmcnt(3)
	v_mfma_f32_32x32x16_bf16 v[96:111], v[128:131], v[162:165], v[96:111]
	v_mfma_f32_32x32x16_bf16 v[112:127], v[142:145], v[162:165], v[112:127]
	v_exp_f32_e32 v78, v78
	v_exp_f32_e32 v79, v79
	v_add_f32_e32 v140, v140, v72
	v_add_f32_e32 v166, v166, v73
	v_add_f32_e32 v140, v140, v74
	v_add_f32_e32 v166, v166, v75
	v_cvt_pk_bf16_f32 v68, v72, v73
	v_cvt_pk_bf16_f32 v69, v74, v75
	v_exp_f32_e32 v80, v80
	v_exp_f32_e32 v81, v81
	v_exp_f32_e32 v82, v82
	v_exp_f32_e32 v83, v83
	v_add_f32_e32 v140, v140, v76
	v_add_f32_e32 v166, v166, v77
	v_add_f32_e32 v140, v140, v78
	v_add_f32_e32 v166, v166, v79
	v_cvt_pk_bf16_f32 v70, v76, v77
	v_cvt_pk_bf16_f32 v71, v78, v79
	v_exp_f32_e32 v84, v84
	v_exp_f32_e32 v85, v85
	v_exp_f32_e32 v86, v86
	v_exp_f32_e32 v87, v87
	v_add_f32_e32 v140, v140, v80
	v_add_f32_e32 v166, v166, v81
	v_add_f32_e32 v140, v140, v82
	v_add_f32_e32 v166, v166, v83
	v_cvt_pk_bf16_f32 v72, v80, v81
	v_cvt_pk_bf16_f32 v73, v82, v83
	s_waitcnt lgkmcnt(0)
	v_mfma_f32_32x32x16_bf16 v[96:111], v[176:179], v[186:189], v[96:111]
	v_mfma_f32_32x32x16_bf16 v[112:127], v[180:183], v[186:189], v[112:127]
	v_exp_f32_e32 v88, v88
	v_exp_f32_e32 v89, v89
	v_exp_f32_e32 v90, v90
	v_exp_f32_e32 v91, v91
	v_add_f32_e32 v140, v140, v84
	v_add_f32_e32 v166, v166, v85
	v_add_f32_e32 v140, v140, v86
	v_add_f32_e32 v166, v166, v87
	v_cvt_pk_bf16_f32 v74, v84, v85
	v_cvt_pk_bf16_f32 v75, v86, v87
	v_exp_f32_e32 v92, v92
	v_exp_f32_e32 v93, v93
	v_exp_f32_e32 v94, v94
	v_exp_f32_e32 v95, v95
	v_add_f32_e32 v140, v140, v88
	v_add_f32_e32 v166, v166, v89
	v_add_f32_e32 v140, v140, v90
	v_add_f32_e32 v166, v166, v91
	v_cvt_pk_bf16_f32 v76, v88, v89
	v_cvt_pk_bf16_f32 v77, v90, v91
	v_add_f32_e32 v140, v140, v92
	v_add_f32_e32 v166, v166, v93
	v_add_f32_e32 v140, v140, v94
	v_add_f32_e32 v166, v166, v95
	v_cvt_pk_bf16_f32 v78, v92, v93
	v_cvt_pk_bf16_f32 v79, v94, v95
	v_add_f32_e32 v140, v140, v166
	s_nop 7
	s_nop 3
	v_max3_f32 v248, v96, v97, v98
	v_max3_f32 v249, v112, v113, v114
	v_max3_f32 v248, v248, v99, v100
	v_max3_f32 v249, v249, v115, v116
	v_max3_f32 v248, v248, v101, v102
	v_max3_f32 v249, v249, v117, v118
	v_max3_f32 v248, v248, v103, v104
	v_max3_f32 v249, v249, v119, v120
	v_max3_f32 v248, v248, v105, v106
	v_max3_f32 v249, v249, v121, v122
	v_max3_f32 v248, v248, v107, v108
	v_max3_f32 v249, v249, v123, v124
	v_max3_f32 v248, v248, v109, v110
	v_max3_f32 v249, v249, v125, v126
	v_max3_f32 v248, v248, v111, v127
	v_max_f32_e32 v248, v248, v249
	v_mov_b32_e32 v251, v248
	s_nop 1
	v_permlane32_swap_b32_e32 v248, v251
	v_max_f32_e32 v167, v248, v251
	v_sub_f32_e32 v96, v96, v167
	v_sub_f32_e32 v97, v97, v167
	v_sub_f32_e32 v98, v98, v167
	v_sub_f32_e32 v99, v99, v167
	v_sub_f32_e32 v100, v100, v167
	v_sub_f32_e32 v101, v101, v167
	v_sub_f32_e32 v102, v102, v167
	v_sub_f32_e32 v103, v103, v167
	v_sub_f32_e32 v104, v104, v167
	v_sub_f32_e32 v105, v105, v167
	v_sub_f32_e32 v106, v106, v167
	v_sub_f32_e32 v107, v107, v167
	v_sub_f32_e32 v108, v108, v167
	v_sub_f32_e32 v109, v109, v167
	v_sub_f32_e32 v110, v110, v167
	v_sub_f32_e32 v111, v111, v167
	v_sub_f32_e32 v112, v112, v167
	v_sub_f32_e32 v113, v113, v167
	v_sub_f32_e32 v114, v114, v167
	v_sub_f32_e32 v115, v115, v167
	v_sub_f32_e32 v116, v116, v167
	v_sub_f32_e32 v117, v117, v167
	v_sub_f32_e32 v118, v118, v167
	v_sub_f32_e32 v119, v119, v167
	v_sub_f32_e32 v120, v120, v167
	v_sub_f32_e32 v121, v121, v167
	v_sub_f32_e32 v122, v122, v167
	v_sub_f32_e32 v123, v123, v167
	v_sub_f32_e32 v124, v124, v167
	v_sub_f32_e32 v125, v125, v167
	v_sub_f32_e32 v126, v126, v167
	v_sub_f32_e32 v127, v127, v167
	v_sub_f32_e32 v190, 0, v167
	v_sub_f32_e32 v191, 0, v167
	v_sub_f32_e32 v192, 0, v167
	v_sub_f32_e32 v193, 0, v167
	v_sub_f32_e32 v194, 0, v167
	v_sub_f32_e32 v195, 0, v167
	v_sub_f32_e32 v196, 0, v167
	v_sub_f32_e32 v197, 0, v167
	v_sub_f32_e32 v198, 0, v167
	v_sub_f32_e32 v199, 0, v167
	v_sub_f32_e32 v200, 0, v167
	v_sub_f32_e32 v201, 0, v167
	v_sub_f32_e32 v202, 0, v167
	v_sub_f32_e32 v203, 0, v167
	v_sub_f32_e32 v204, 0, v167
	v_sub_f32_e32 v205, 0, v167
	s_waitcnt vmcnt(0)
	ds_write_b128 v150, v[218:221] offset:21504
	ds_write_b128 v159, v[222:225]
	s_waitcnt lgkmcnt(0)
	s_barrier
; #define LAS __attribute__((address_space(3)))
; __device__ __forceinline__ float max2_(float a, float b) { return __builtin_amdgcn_fmed3f(a, b, INFINITY); }
; __device__ __forceinline__ void softmax_blk(f32x16& p0, f32x16& p1, f32x16& o0, f32x16& o1, float& mhat, float& lrun, u32x4 (&pf)[4], bool first) {
;     float r0 = max2_(p0[0], p0[1]), r1 = max2_(p1[0], p1[1]);
; #pragma unroll
;     for (int e = 2; e < 16; ++e) { r0 = max2_(r0, p0[e]); r1 = max2_(r1, p1[e]); }
;     const float rm = swap_max(max2_(r0, r1));
;     if (first || __any(rm - mhat > THR)) {
;         const float mn = first ? rm : fmaxf(rm, mhat); const float f = first ? 0.f : __builtin_amdgcn_exp2f(mhat - mn); mhat = mn; lrun *= f;
; #pragma unroll
;         for (int e = 0; e < 16; ++e) { o0[e] *= f; o1[e] *= f; }
;     }
;     float s0 = 0.f, s1 = 0.f;
; #pragma unroll
;     for (int e = 0; e < 16; ++e) { p0[e] = __builtin_amdgcn_exp2f(p0[e] - mhat); p1[e] = __builtin_amdgcn_exp2f(p1[e] - mhat); s0 += p0[e]; s1 += p1[e]; }
;     lrun += s0 + s1;
;     pf[0] = MLA_PACK(p0, 0); pf[1] = MLA_PACK(p0, 8); pf[2] = MLA_PACK(p1, 0); pf[3] = MLA_PACK(p1, 8);
; }
; __device__ __forceinline__ void pv_blk(const u32x4 (&pf)[4], f32x16& o0, f32x16& o1, LAS const unsigned char* vbase) {
; #pragma unroll
;     for (int ks = 0; ks < 4; ++ks) {
;         const bf16x8 p = __builtin_bit_cast(bf16x8, pf[ks]);
;         { const s16x4 lo = vtr(vbase + ks * 1024), hh = vtr(vbase + ks * 1024 + 512); const bf16x8 vf = {lo[0], lo[1], lo[2], lo[3], hh[0], hh[1], hh[2], hh[3]};
;           o0 = __builtin_amdgcn_mfma_f32_32x32x16_bf16(vf, p, o0, 0, 0, 0); }
;         { const s16x4 lo = vtr(vbase + 4096 + ks * 1024), hh = vtr(vbase + 4096 + ks * 1024 + 512); const bf16x8 vf = {lo[0], lo[1], lo[2], lo[3], hh[0], hh[1], hh[2], hh[3]};
;           o1 = __builtin_amdgcn_mfma_f32_32x32x16_bf16(vf, p, o1, 0, 0, 0); }
;     }
; }
; __device__ __forceinline__ void attn_unit(const bf16_t* Qh, const bf16_t* Kh, const bf16_t* Vh, bf16_t* Oh  , int S, int qb, LAS unsigned char* lds, int tid) {
;     ...
;     for (int t = 0; t < NT; ++t) {
;         const unsigned cur = (unsigned)(t & 1) * BUF, nxt = BUF - cur;
;         const int tn = t + 1 < NT ? t + 1 : t;
;         ka = GLD(u32x4, Kg + (size_t)tn * 768 + kc0); kb = GLD(u32x4, Kg + (size_t)tn * 768 + kc1); va = GLD(u32x4, Vg + (size_t)tn * 512 + tid);
.Lmla_top:
	ds_read_b64_tr_b16 v[128:129], v158 offset:13312
	ds_read_b64_tr_b16 v[130:131], v158 offset:13824
	ds_read_b64_tr_b16 v[142:143], v158 offset:17408
	ds_read_b64_tr_b16 v[144:145], v158 offset:17920
	ds_read_b64_tr_b16 v[176:177], v158 offset:14336
	ds_read_b64_tr_b16 v[178:179], v158 offset:14848
	ds_read_b64_tr_b16 v[180:181], v158 offset:18432
	ds_read_b64_tr_b16 v[182:183], v158 offset:18944
	s_waitcnt lgkmcnt(4)
	v_mfma_f32_32x32x16_bf16 v[16:31], v[128:131], v[64:67], v[16:31]
	v_mfma_f32_32x32x16_bf16 v[0:15], v[142:145], v[64:67], v[0:15]
	ds_read_b64_tr_b16 v[128:129], v158 offset:15360
	ds_read_b64_tr_b16 v[130:131], v158 offset:15872
	ds_read_b64_tr_b16 v[142:143], v158 offset:19456
	ds_read_b64_tr_b16 v[144:145], v158 offset:19968
	global_load_dwordx4 v[218:221], v171, s[26:27]
	global_load_dwordx4 v[222:225], v184, s[26:27]
	global_load_dwordx4 v[226:229], v146, s[100:101]
	s_add_u32 s26, s26, 0x3000
	s_addc_u32 s27, s27, 0
	s_add_u32 s100, s100, 0x2000
	s_addc_u32 s101, s101, 0
	v_max3_f32 v248, v96, v97, v98
	v_max3_f32 v249, v112, v113, v114
	v_max3_f32 v248, v248, v99, v100
	v_max3_f32 v249, v249, v115, v116
	v_max3_f32 v248, v248, v101, v102
	v_max3_f32 v249, v249, v117, v118
	v_max3_f32 v248, v248, v103, v104
	v_max3_f32 v249, v249, v119, v120
	v_max3_f32 v248, v248, v105, v106
	v_max3_f32 v249, v249, v121, v122
	s_waitcnt lgkmcnt(4)
	v_mfma_f32_32x32x16_bf16 v[16:31], v[176:179], v[68:71], v[16:31]
	v_mfma_f32_32x32x16_bf16 v[0:15], v[180:183], v[68:71], v[0:15]
	ds_read_b64_tr_b16 v[176:177], v158 offset:16384
	ds_read_b64_tr_b16 v[178:179], v158 offset:16896
	ds_read_b64_tr_b16 v[180:181], v158 offset:20480
	ds_read_b64_tr_b16 v[182:183], v158 offset:20992
	v_max3_f32 v248, v248, v107, v108
	v_max3_f32 v249, v249, v123, v124
	v_max3_f32 v248, v248, v109, v110
	v_max3_f32 v249, v249, v125, v126
	v_max3_f32 v248, v248, v111, v127
	v_max_f32_e32 v248, v248, v249
	v_cmp_lt_f32_e32 vcc, s72, v248
	s_cbranch_vccnz .Lmla_rescBo
.Lmla_rescBo_back:
	v_exp_f32_e32 v96, v96
	v_exp_f32_e32 v97, v97
	s_waitcnt lgkmcnt(4)
	v_mfma_f32_32x32x16_bf16 v[16:31], v[128:131], v[72:75], v[16:31]
	v_mfma_f32_32x32x16_bf16 v[0:15], v[142:145], v[72:75], v[0:15]
	ds_read_b128 v[128:131], v155 offset:21504
	ds_read_b128 v[142:145], v155 offset:28160
	ds_read_b128 v[162:165], v135 offset:43008
	v_exp_f32_e32 v98, v98
	v_exp_f32_e32 v99, v99
	v_exp_f32_e32 v100, v100
	v_exp_f32_e32 v101, v101
	v_exp_f32_e32 v102, v102
	v_exp_f32_e32 v103, v103
	v_add_f32_e32 v166, v96, v97
	v_add_f32_e32 v141, v141, v98
	v_add_f32_e32 v166, v166, v99
	v_cvt_pk_bf16_f32 v96, v96, v97
	s_waitcnt lgkmcnt(3)
	v_mfma_f32_32x32x16_bf16 v[16:31], v[176:179], v[76:79], v[16:31]
	v_mfma_f32_32x32x16_bf16 v[0:15], v[180:183], v[76:79], v[0:15]
	ds_read_b128 v[176:179], v155 offset:21536
	ds_read_b128 v[180:183], v155 offset:28192
	ds_read_b128 v[186:189], v135 offset:44032
	v_cvt_pk_bf16_f32 v97, v98, v99
	v_exp_f32_e32 v104, v104
	v_exp_f32_e32 v105, v105
	v_exp_f32_e32 v106, v106
	v_exp_f32_e32 v107, v107
	v_add_f32_e32 v141, v141, v100
	v_add_f32_e32 v166, v166, v101
	v_add_f32_e32 v141, v141, v102
	v_add_f32_e32 v166, v166, v103
	v_cvt_pk_bf16_f32 v98, v100, v101
	s_waitcnt lgkmcnt(3)
	v_mfma_f32_32x32x16_bf16 v[64:79], v[128:131], v[162:165], v[232:247]
	v_mfma_f32_32x32x16_bf16 v[80:95], v[142:145], v[162:165], v[232:247]
	ds_read_b128 v[128:131], v155 offset:21568
	ds_read_b128 v[142:145], v155 offset:28224
	ds_read_b128 v[162:165], v135 offset:45056
	v_cvt_pk_bf16_f32 v99, v102, v103
	v_exp_f32_e32 v108, v108
	v_exp_f32_e32 v109, v109
	v_exp_f32_e32 v110, v110
	v_exp_f32_e32 v111, v111
	v_add_f32_e32 v141, v141, v104
	v_add_f32_e32 v166, v166, v105
	v_add_f32_e32 v141, v141, v106
	v_add_f32_e32 v166, v166, v107
	s_waitcnt lgkmcnt(3)
	v_mfma_f32_32x32x16_bf16 v[64:79], v[176:179], v[186:189], v[64:79]
	v_mfma_f32_32x32x16_bf16 v[80:95], v[180:183], v[186:189], v[80:95]
	ds_read_b128 v[176:179], v155 offset:21600
	ds_read_b128 v[180:183], v155 offset:28256
	ds_read_b128 v[186:189], v135 offset:46080
	v_cvt_pk_bf16_f32 v100, v104, v105
	v_cvt_pk_bf16_f32 v101, v106, v107
	v_exp_f32_e32 v112, v112
	v_exp_f32_e32 v113, v113
	v_exp_f32_e32 v114, v114
	v_exp_f32_e32 v115, v115
	v_add_f32_e32 v141, v141, v108
	v_add_f32_e32 v166, v166, v109
	v_add_f32_e32 v141, v141, v110
	v_add_f32_e32 v166, v166, v111
	s_waitcnt lgkmcnt(3)
	v_mfma_f32_32x32x16_bf16 v[64:79], v[128:131], v[162:165], v[64:79]
	v_mfma_f32_32x32x16_bf16 v[80:95], v[142:145], v[162:165], v[80:95]
	ds_read_b128 v[128:131], v155 offset:21632
	ds_read_b128 v[142:145], v155 offset:28288
	ds_read_b128 v[162:165], v135 offset:47104
	v_cvt_pk_bf16_f32 v102, v108, v109
	v_cvt_pk_bf16_f32 v103, v110, v111
	v_exp_f32_e32 v116, v116
	v_exp_f32_e32 v117, v117
	v_exp_f32_e32 v118, v118
	v_exp_f32_e32 v119, v119
	v_add_f32_e32 v141, v141, v112
	v_add_f32_e32 v166, v166, v113
	v_add_f32_e32 v141, v141, v114
	v_add_f32_e32 v166, v166, v115
	s_waitcnt lgkmcnt(3)
	v_mfma_f32_32x32x16_bf16 v[64:79], v[176:179], v[186:189], v[64:79]
	v_mfma_f32_32x32x16_bf16 v[80:95], v[180:183], v[186:189], v[80:95]
	ds_read_b128 v[176:179], v155 offset:21664
	ds_read_b128 v[180:183], v155 offset:28320
	ds_read_b128 v[186:189], v135 offset:48128
	v_cvt_pk_bf16_f32 v104, v112, v113
	v_cvt_pk_bf16_f32 v105, v114, v115
	v_exp_f32_e32 v120, v120
	v_exp_f32_e32 v121, v121
	v_exp_f32_e32 v122, v122
	v_exp_f32_e32 v123, v123
	v_add_f32_e32 v141, v141, v116
	v_add_f32_e32 v166, v166, v117
	v_add_f32_e32 v141, v141, v118
	v_add_f32_e32 v166, v166, v119
	s_waitcnt lgkmcnt(3)
; __device__ __forceinline__ void softmax_blk(f32x16& p0, f32x16& p1, f32x16& o0, f32x16& o1, float& mhat, float& lrun, u32x4 (&pf)[4], bool first) {
;     float r0 = max2_(p0[0], p0[1]), r1 = max2_(p1[0], p1[1]);
; #pragma unroll
;     for (int e = 2; e < 16; ++e) { r0 = max2_(r0, p0[e]); r1 = max2_(r1, p1[e]); }
;     const float rm = swap_max(max2_(r0, r1));
;     if (first || __any(rm - mhat > THR)) {
;         const float mn = first ? rm : fmaxf(rm, mhat); const float f = first ? 0.f : __builtin_amdgcn_exp2f(mhat - mn); mhat = mn; lrun *= f;
; #pragma unroll
;         for (int e = 0; e < 16; ++e) { o0[e] *= f; o1[e] *= f; }
;     }
;     float s0 = 0.f, s1 = 0.f;
; #pragma unroll
;     for (int e = 0; e < 16; ++e) { p0[e] = __builtin_amdgcn_exp2f(p0[e] - mhat); p1[e] = __builtin_amdgcn_exp2f(p1[e] - mhat); s0 += p0[e]; s1 += p1[e]; }
;     lrun += s0 + s1;
;     pf[0] = MLA_PACK(p0, 0); pf[1] = MLA_PACK(p0, 8); pf[2] = MLA_PACK(p1, 0); pf[3] = MLA_PACK(p1, 8);
; }
; __device__ __forceinline__ void pv_blk(const u32x4 (&pf)[4], f32x16& o0, f32x16& o1, LAS const unsigned char* vbase) {
; #pragma unroll
;     for (int ks = 0; ks < 4; ++ks) {
;         const bf16x8 p = __builtin_bit_cast(bf16x8, pf[ks]);
;         { const s16x4 lo = vtr(vbase + ks * 1024), hh = vtr(vbase + ks * 1024 + 512); const bf16x8 vf = {lo[0], lo[1], lo[2], lo[3], hh[0], hh[1], hh[2], hh[3]};
;           o0 = __builtin_amdgcn_mfma_f32_32x32x16_bf16(vf, p, o0, 0, 0, 0); }
;         { const s16x4 lo = vtr(vbase + 4096 + ks * 1024), hh = vtr(vbase + 4096 + ks * 1024 + 512); const bf16x8 vf = {lo[0], lo[1], lo[2], lo[3], hh[0], hh[1], hh[2], hh[3]};
;           o1 = __builtin_amdgcn_mfma_f32_32x32x16_bf16(vf, p, o1, 0, 0, 0); }
;     }
; }
; __device__ __forceinline__ void attn_unit(const bf16_t* Qh, const bf16_t* Kh, const bf16_t* Vh, bf16_t* Oh  , int S, int qb, LAS unsigned char* lds, int tid) {
;     ...
;         {
;             f32x16 p0 = {}, p1 = {};
; #pragma unroll
;             for (int s = 0; s < 6; ++s) {
;                 const bf16x8 a0 = *(const LAS bf16x8*)(lds + cur + kfo + s * 32), a1 = *(const LAS bf16x8*)(lds + cur + kfo + 32 * KPITCH + s * 32);
;                 const bf16x8 q = *(const LAS bf16x8*)(ql + (6 + s) * 1024);
;                 p0 = __builtin_amdgcn_mfma_f32_32x32x16_bf16(a0, q, p0, 0, 0, 0); p1 = __builtin_amdgcn_mfma_f32_32x32x16_bf16(a1, q, p1, 0, 0, 0);
	v_mfma_f32_32x32x16_bf16 v[64:79], v[128:131], v[162:165], v[64:79]
	v_mfma_f32_32x32x16_bf16 v[80:95], v[142:145], v[162:165], v[80:95]
	ds_read_b64_tr_b16 v[128:129], v158 offset:13312
	ds_read_b64_tr_b16 v[130:131], v158 offset:13824
	ds_read_b64_tr_b16 v[142:143], v158 offset:17408
	ds_read_b64_tr_b16 v[144:145], v158 offset:17920
	v_cvt_pk_bf16_f32 v106, v116, v117
	v_cvt_pk_bf16_f32 v107, v118, v119
	v_exp_f32_e32 v124, v124
	v_exp_f32_e32 v125, v125
	v_exp_f32_e32 v126, v126
	v_exp_f32_e32 v127, v127
	v_add_f32_e32 v141, v141, v120
	v_add_f32_e32 v166, v166, v121
	v_add_f32_e32 v141, v141, v122
	v_add_f32_e32 v166, v166, v123
	s_waitcnt lgkmcnt(4)
	v_mfma_f32_32x32x16_bf16 v[64:79], v[176:179], v[186:189], v[64:79]
	v_mfma_f32_32x32x16_bf16 v[80:95], v[180:183], v[186:189], v[80:95]
	ds_read_b64_tr_b16 v[176:177], v158 offset:14336
	ds_read_b64_tr_b16 v[178:179], v158 offset:14848
	ds_read_b64_tr_b16 v[180:181], v158 offset:18432
	ds_read_b64_tr_b16 v[182:183], v158 offset:18944
	v_cvt_pk_bf16_f32 v108, v120, v121
	v_cvt_pk_bf16_f32 v109, v122, v123
	v_add_f32_e32 v141, v141, v124
	v_add_f32_e32 v166, v166, v125
	v_add_f32_e32 v141, v141, v126
	v_add_f32_e32 v166, v166, v127
	v_cvt_pk_bf16_f32 v110, v124, v125
	v_cvt_pk_bf16_f32 v111, v126, v127
	v_add_f32_e32 v141, v141, v166
	s_waitcnt lgkmcnt(4)
	v_mfma_f32_32x32x16_bf16 v[48:63], v[128:131], v[96:99], v[48:63]
	v_mfma_f32_32x32x16_bf16 v[32:47], v[142:145], v[96:99], v[32:47]
	ds_read_b64_tr_b16 v[128:129], v158 offset:15360
	ds_read_b64_tr_b16 v[130:131], v158 offset:15872
	ds_read_b64_tr_b16 v[142:143], v158 offset:19456
	ds_read_b64_tr_b16 v[144:145], v158 offset:19968
	v_max3_f32 v248, v64, v65, v66
	v_max3_f32 v249, v80, v81, v82
	v_max3_f32 v248, v248, v67, v68
	v_max3_f32 v249, v249, v83, v84
	v_max3_f32 v248, v248, v69, v70
	v_max3_f32 v249, v249, v85, v86
	v_max3_f32 v248, v248, v71, v72
	v_max3_f32 v249, v249, v87, v88
	v_max3_f32 v248, v248, v73, v74
	v_max3_f32 v249, v249, v89, v90
	s_waitcnt lgkmcnt(4)
	v_mfma_f32_32x32x16_bf16 v[48:63], v[176:179], v[100:103], v[48:63]
	v_mfma_f32_32x32x16_bf16 v[32:47], v[180:183], v[100:103], v[32:47]
	ds_read_b64_tr_b16 v[176:177], v158 offset:16384
	ds_read_b64_tr_b16 v[178:179], v158 offset:16896
	ds_read_b64_tr_b16 v[180:181], v158 offset:20480
	ds_read_b64_tr_b16 v[182:183], v158 offset:20992
	v_max3_f32 v248, v248, v75, v76
	v_max3_f32 v249, v249, v91, v92
	v_max3_f32 v248, v248, v77, v78
	v_max3_f32 v249, v249, v93, v94
	v_max3_f32 v248, v248, v79, v95
	v_max_f32_e32 v248, v248, v249
	v_cmp_lt_f32_e32 vcc, s72, v248
	s_cbranch_vccnz .Lmla_rescAo
.Lmla_rescAo_back:
	v_exp_f32_e32 v64, v64
	v_exp_f32_e32 v65, v65
	s_waitcnt lgkmcnt(4)
	v_mfma_f32_32x32x16_bf16 v[48:63], v[128:131], v[104:107], v[48:63]
	v_mfma_f32_32x32x16_bf16 v[32:47], v[142:145], v[104:107], v[32:47]
	ds_read_b128 v[128:131], v155 offset:21504
	ds_read_b128 v[142:145], v155 offset:28160
	ds_read_b128 v[162:165], v135 offset:49152
	v_exp_f32_e32 v66, v66
	v_exp_f32_e32 v67, v67
	v_exp_f32_e32 v68, v68
	v_exp_f32_e32 v69, v69
	v_exp_f32_e32 v70, v70
	v_exp_f32_e32 v71, v71
	v_add_f32_e32 v166, v64, v65
	v_add_f32_e32 v140, v140, v66
	v_add_f32_e32 v166, v166, v67
	v_cvt_pk_bf16_f32 v64, v64, v65
	s_waitcnt lgkmcnt(3)
	v_mfma_f32_32x32x16_bf16 v[48:63], v[176:179], v[108:111], v[48:63]
	v_mfma_f32_32x32x16_bf16 v[32:47], v[180:183], v[108:111], v[32:47]
	ds_read_b128 v[176:179], v155 offset:21536
	ds_read_b128 v[180:183], v155 offset:28192
	ds_read_b128 v[186:189], v135 offset:50176
	v_cvt_pk_bf16_f32 v65, v66, v67
	v_exp_f32_e32 v72, v72
	v_exp_f32_e32 v73, v73
	v_exp_f32_e32 v74, v74
	v_exp_f32_e32 v75, v75
	v_add_f32_e32 v140, v140, v68
	v_add_f32_e32 v166, v166, v69
	v_add_f32_e32 v140, v140, v70
	v_add_f32_e32 v166, v166, v71
	v_cvt_pk_bf16_f32 v66, v68, v69
	s_waitcnt lgkmcnt(3)
	v_mfma_f32_32x32x16_bf16 v[96:111], v[128:131], v[162:165], v[190:205]
	v_mfma_f32_32x32x16_bf16 v[112:127], v[142:145], v[162:165], v[190:205]
	ds_read_b128 v[128:131], v155 offset:21568
	ds_read_b128 v[142:145], v155 offset:28224
	ds_read_b128 v[162:165], v135 offset:51200
	v_cvt_pk_bf16_f32 v67, v70, v71
	v_exp_f32_e32 v76, v76
	v_exp_f32_e32 v77, v77
	v_exp_f32_e32 v78, v78
	v_exp_f32_e32 v79, v79
	v_add_f32_e32 v140, v140, v72
	v_add_f32_e32 v166, v166, v73
	v_add_f32_e32 v140, v140, v74
	v_add_f32_e32 v166, v166, v75
	s_waitcnt lgkmcnt(3)
	v_mfma_f32_32x32x16_bf16 v[96:111], v[176:179], v[186:189], v[96:111]
	v_mfma_f32_32x32x16_bf16 v[112:127], v[180:183], v[186:189], v[112:127]
	ds_read_b128 v[176:179], v155 offset:21600
	ds_read_b128 v[180:183], v155 offset:28256
	ds_read_b128 v[186:189], v135 offset:52224
	v_cvt_pk_bf16_f32 v68, v72, v73
	v_cvt_pk_bf16_f32 v69, v74, v75
	v_exp_f32_e32 v80, v80
	v_exp_f32_e32 v81, v81
	v_exp_f32_e32 v82, v82
	v_exp_f32_e32 v83, v83
	v_add_f32_e32 v140, v140, v76
	v_add_f32_e32 v166, v166, v77
	v_add_f32_e32 v140, v140, v78
	v_add_f32_e32 v166, v166, v79
	s_waitcnt lgkmcnt(3)
	v_mfma_f32_32x32x16_bf16 v[96:111], v[128:131], v[162:165], v[96:111]
	v_mfma_f32_32x32x16_bf16 v[112:127], v[142:145], v[162:165], v[112:127]
	ds_read_b128 v[128:131], v155 offset:21632
	ds_read_b128 v[142:145], v155 offset:28288
	ds_read_b128 v[162:165], v135 offset:53248
	v_cvt_pk_bf16_f32 v70, v76, v77
	v_cvt_pk_bf16_f32 v71, v78, v79
	v_exp_f32_e32 v84, v84
	v_exp_f32_e32 v85, v85
	v_exp_f32_e32 v86, v86
	v_exp_f32_e32 v87, v87
	v_add_f32_e32 v140, v140, v80
	v_add_f32_e32 v166, v166, v81
	v_add_f32_e32 v140, v140, v82
	v_add_f32_e32 v166, v166, v83
	s_waitcnt lgkmcnt(3)
; #define LAS __attribute__((address_space(3)))
; __device__ __forceinline__ s16x4 vtr(LAS const unsigned char* p) { return __builtin_bit_cast(s16x4, __builtin_amdgcn_ds_read_tr16_b64_v4i16((LAS s16x4*)p)); }
; __device__ __forceinline__ void softmax_blk(f32x16& p0, f32x16& p1, f32x16& o0, f32x16& o1, float& mhat, float& lrun, u32x4 (&pf)[4], bool first) {
;     ...
;     for (int e = 0; e < 16; ++e) { p0[e] = __builtin_amdgcn_exp2f(p0[e] - mhat); p1[e] = __builtin_amdgcn_exp2f(p1[e] - mhat); s0 += p0[e]; s1 += p1[e]; }
;     lrun += s0 + s1;
;     pf[0] = MLA_PACK(p0, 0); pf[1] = MLA_PACK(p0, 8); pf[2] = MLA_PACK(p1, 0); pf[3] = MLA_PACK(p1, 8);
; }
; __device__ __forceinline__ void pv_blk(const u32x4 (&pf)[4], f32x16& o0, f32x16& o1, LAS const unsigned char* vbase) {
; #pragma unroll
;     for (int ks = 0; ks < 4; ++ks) {
;         const bf16x8 p = __builtin_bit_cast(bf16x8, pf[ks]);
;         { const s16x4 lo = vtr(vbase + ks * 1024), hh = vtr(vbase + ks * 1024 + 512); const bf16x8 vf = {lo[0], lo[1], lo[2], lo[3], hh[0], hh[1], hh[2], hh[3]};
;           o0 = __builtin_amdgcn_mfma_f32_32x32x16_bf16(vf, p, o0, 0, 0, 0); }
;         { const s16x4 lo = vtr(vbase + 4096 + ks * 1024), hh = vtr(vbase + 4096 + ks * 1024 + 512); const bf16x8 vf = {lo[0], lo[1], lo[2], lo[3], hh[0], hh[1], hh[2], hh[3]};
;           o1 = __builtin_amdgcn_mfma_f32_32x32x16_bf16(vf, p, o1, 0, 0, 0); }
;     }
; }
; __device__ __forceinline__ void attn_unit(const bf16_t* Qh, const bf16_t* Kh, const bf16_t* Vh, bf16_t* Oh  , int S, int qb, LAS unsigned char* lds, int tid) {
;     ...
;         {
;             f32x16 p0 = {}, p1 = {};
; #pragma unroll
;             for (int s = 0; s < 6; ++s) {
;                 const bf16x8 a0 = *(const LAS bf16x8*)(lds + cur + kfo + s * 32), a1 = *(const LAS bf16x8*)(lds + cur + kfo + 32 * KPITCH + s * 32);
;                 const bf16x8 q = *(const LAS bf16x8*)(ql + (6 + s) * 1024);
;                 p0 = __builtin_amdgcn_mfma_f32_32x32x16_bf16(a0, q, p0, 0, 0, 0); p1 = __builtin_amdgcn_mfma_f32_32x32x16_bf16(a1, q, p1, 0, 0, 0);
;             }
;             softmax_blk(p0, p1, ob0, ob1, mb, lb, pf, t == 0);
;             pv_blk(pf, ob0, ob1, lds + cur + vb);
;         }
;         *(LAS u32x4*)(lds + nxt + kd0) = ka; *(LAS u32x4*)(lds + (has1 ? nxt : 0u) + kd1) = kb; *(LAS u32x4*)(lds + nxt + vd) = va;
;         __syncthreads();
	v_mfma_f32_32x32x16_bf16 v[96:111], v[176:179], v[186:189], v[96:111]
	v_mfma_f32_32x32x16_bf16 v[112:127], v[180:183], v[186:189], v[112:127]
	ds_read_b128 v[176:179], v155 offset:21664
	ds_read_b128 v[180:183], v155 offset:28320
	ds_read_b128 v[186:189], v135 offset:54272
	v_cvt_pk_bf16_f32 v72, v80, v81
	v_cvt_pk_bf16_f32 v73, v82, v83
	v_exp_f32_e32 v88, v88
	v_exp_f32_e32 v89, v89
	v_exp_f32_e32 v90, v90
	v_exp_f32_e32 v91, v91
	v_add_f32_e32 v140, v140, v84
	v_add_f32_e32 v166, v166, v85
	v_add_f32_e32 v140, v140, v86
	v_add_f32_e32 v166, v166, v87
	s_waitcnt vmcnt(0)
	ds_write_b128 v150, v[218:221]
	ds_write_b128 v156, v[222:225]
	ds_write_b128 v157, v[226:229] offset:34816
	s_waitcnt lgkmcnt(6)
	v_mfma_f32_32x32x16_bf16 v[96:111], v[128:131], v[162:165], v[96:111]
	v_mfma_f32_32x32x16_bf16 v[112:127], v[142:145], v[162:165], v[112:127]
	v_cvt_pk_bf16_f32 v74, v84, v85
	v_cvt_pk_bf16_f32 v75, v86, v87
	v_exp_f32_e32 v92, v92
	v_exp_f32_e32 v93, v93
	v_exp_f32_e32 v94, v94
	v_exp_f32_e32 v95, v95
	v_add_f32_e32 v140, v140, v88
	v_add_f32_e32 v166, v166, v89
	v_add_f32_e32 v140, v140, v90
	v_add_f32_e32 v166, v166, v91
	s_waitcnt lgkmcnt(3)
	v_mfma_f32_32x32x16_bf16 v[96:111], v[176:179], v[186:189], v[96:111]
	v_mfma_f32_32x32x16_bf16 v[112:127], v[180:183], v[186:189], v[112:127]
	v_cvt_pk_bf16_f32 v76, v88, v89
	v_cvt_pk_bf16_f32 v77, v90, v91
	v_add_f32_e32 v140, v140, v92
	v_add_f32_e32 v166, v166, v93
	v_add_f32_e32 v140, v140, v94
	v_add_f32_e32 v166, v166, v95
	v_cvt_pk_bf16_f32 v78, v92, v93
	v_cvt_pk_bf16_f32 v79, v94, v95
	v_add_f32_e32 v140, v140, v166
	s_waitcnt lgkmcnt(0)
	s_barrier
	s_add_i32 s1, s1, 1
	s_cmp_lg_u32 s1, s18
	s_cbranch_scc0 .Lmla_epi
	ds_read_b64_tr_b16 v[128:129], v158 offset:34816
	ds_read_b64_tr_b16 v[130:131], v158 offset:35328
	ds_read_b64_tr_b16 v[142:143], v158 offset:38912
	ds_read_b64_tr_b16 v[144:145], v158 offset:39424
	ds_read_b64_tr_b16 v[176:177], v158 offset:35840
	ds_read_b64_tr_b16 v[178:179], v158 offset:36352
	ds_read_b64_tr_b16 v[180:181], v158 offset:39936
	ds_read_b64_tr_b16 v[182:183], v158 offset:40448
	s_waitcnt lgkmcnt(4)
	v_mfma_f32_32x32x16_bf16 v[16:31], v[128:131], v[64:67], v[16:31]
	v_mfma_f32_32x32x16_bf16 v[0:15], v[142:145], v[64:67], v[0:15]
	ds_read_b64_tr_b16 v[128:129], v158 offset:36864
	ds_read_b64_tr_b16 v[130:131], v158 offset:37376
	ds_read_b64_tr_b16 v[142:143], v158 offset:40960
	ds_read_b64_tr_b16 v[144:145], v158 offset:41472
	global_load_dwordx4 v[218:221], v171, s[26:27]
	global_load_dwordx4 v[222:225], v184, s[26:27]
	global_load_dwordx4 v[226:229], v146, s[100:101]
	s_add_u32 s26, s26, 0x3000
	s_addc_u32 s27, s27, 0
	s_add_u32 s100, s100, 0x2000
	s_addc_u32 s101, s101, 0
	v_max3_f32 v248, v96, v97, v98
	v_max3_f32 v249, v112, v113, v114
	v_max3_f32 v248, v248, v99, v100
	v_max3_f32 v249, v249, v115, v116
	v_max3_f32 v248, v248, v101, v102
	v_max3_f32 v249, v249, v117, v118
	v_max3_f32 v248, v248, v103, v104
	v_max3_f32 v249, v249, v119, v120
	v_max3_f32 v248, v248, v105, v106
	v_max3_f32 v249, v249, v121, v122
	s_waitcnt lgkmcnt(4)
	v_mfma_f32_32x32x16_bf16 v[16:31], v[176:179], v[68:71], v[16:31]
	v_mfma_f32_32x32x16_bf16 v[0:15], v[180:183], v[68:71], v[0:15]
	ds_read_b64_tr_b16 v[176:177], v158 offset:37888
	ds_read_b64_tr_b16 v[178:179], v158 offset:38400
	ds_read_b64_tr_b16 v[180:181], v158 offset:41984
	ds_read_b64_tr_b16 v[182:183], v158 offset:42496
	v_max3_f32 v248, v248, v107, v108
	v_max3_f32 v249, v249, v123, v124
	v_max3_f32 v248, v248, v109, v110
	v_max3_f32 v249, v249, v125, v126
	v_max3_f32 v248, v248, v111, v127
	v_max_f32_e32 v248, v248, v249
	v_cmp_lt_f32_e32 vcc, s72, v248
	s_cbranch_vccnz .Lmla_rescBv
.Lmla_rescBv_back:
	v_exp_f32_e32 v96, v96
	v_exp_f32_e32 v97, v97
	s_waitcnt lgkmcnt(4)
	v_mfma_f32_32x32x16_bf16 v[16:31], v[128:131], v[72:75], v[16:31]
	v_mfma_f32_32x32x16_bf16 v[0:15], v[142:145], v[72:75], v[0:15]
	ds_read_b128 v[128:131], v155
	ds_read_b128 v[142:145], v155 offset:6656
	ds_read_b128 v[162:165], v135 offset:43008
	v_exp_f32_e32 v98, v98
	v_exp_f32_e32 v99, v99
	v_exp_f32_e32 v100, v100
	v_exp_f32_e32 v101, v101
	v_exp_f32_e32 v102, v102
	v_exp_f32_e32 v103, v103
	v_add_f32_e32 v166, v96, v97
	v_add_f32_e32 v141, v141, v98
	v_add_f32_e32 v166, v166, v99
	v_cvt_pk_bf16_f32 v96, v96, v97
	s_waitcnt lgkmcnt(3)
	v_mfma_f32_32x32x16_bf16 v[16:31], v[176:179], v[76:79], v[16:31]
	v_mfma_f32_32x32x16_bf16 v[0:15], v[180:183], v[76:79], v[0:15]
	ds_read_b128 v[176:179], v155 offset:32
	ds_read_b128 v[180:183], v155 offset:6688
	ds_read_b128 v[186:189], v135 offset:44032
	v_cvt_pk_bf16_f32 v97, v98, v99
	v_exp_f32_e32 v104, v104
	v_exp_f32_e32 v105, v105
	v_exp_f32_e32 v106, v106
	v_exp_f32_e32 v107, v107
	v_add_f32_e32 v141, v141, v100
	v_add_f32_e32 v166, v166, v101
	v_add_f32_e32 v141, v141, v102
	v_add_f32_e32 v166, v166, v103
	v_cvt_pk_bf16_f32 v98, v100, v101
	s_waitcnt lgkmcnt(3)
	v_mfma_f32_32x32x16_bf16 v[64:79], v[128:131], v[162:165], v[232:247]
	v_mfma_f32_32x32x16_bf16 v[80:95], v[142:145], v[162:165], v[232:247]
	ds_read_b128 v[128:131], v155 offset:64
	ds_read_b128 v[142:145], v155 offset:6720
	ds_read_b128 v[162:165], v135 offset:45056
	v_cvt_pk_bf16_f32 v99, v102, v103
	v_exp_f32_e32 v108, v108
	v_exp_f32_e32 v109, v109
	v_exp_f32_e32 v110, v110
	v_exp_f32_e32 v111, v111
	v_add_f32_e32 v141, v141, v104
	v_add_f32_e32 v166, v166, v105
	v_add_f32_e32 v141, v141, v106
	v_add_f32_e32 v166, v166, v107
	s_waitcnt lgkmcnt(3)
; __device__ __forceinline__ void softmax_blk(f32x16& p0, f32x16& p1, f32x16& o0, f32x16& o1, float& mhat, float& lrun, u32x4 (&pf)[4], bool first) {
;     float r0 = max2_(p0[0], p0[1]), r1 = max2_(p1[0], p1[1]);
; #pragma unroll
;     for (int e = 2; e < 16; ++e) { r0 = max2_(r0, p0[e]); r1 = max2_(r1, p1[e]); }
;     const float rm = swap_max(max2_(r0, r1));
;     if (first || __any(rm - mhat > THR)) {
;         const float mn = first ? rm : fmaxf(rm, mhat); const float f = first ? 0.f : __builtin_amdgcn_exp2f(mhat - mn); mhat = mn; lrun *= f;
; #pragma unroll
;         for (int e = 0; e < 16; ++e) { o0[e] *= f; o1[e] *= f; }
;     }
;     float s0 = 0.f, s1 = 0.f;
; #pragma unroll
;     for (int e = 0; e < 16; ++e) { p0[e] = __builtin_amdgcn_exp2f(p0[e] - mhat); p1[e] = __builtin_amdgcn_exp2f(p1[e] - mhat); s0 += p0[e]; s1 += p1[e]; }
;     lrun += s0 + s1;
;     pf[0] = MLA_PACK(p0, 0); pf[1] = MLA_PACK(p0, 8); pf[2] = MLA_PACK(p1, 0); pf[3] = MLA_PACK(p1, 8);
; }
; __device__ __forceinline__ void pv_blk(const u32x4 (&pf)[4], f32x16& o0, f32x16& o1, LAS const unsigned char* vbase) {
; #pragma unroll
;     for (int ks = 0; ks < 4; ++ks) {
;         const bf16x8 p = __builtin_bit_cast(bf16x8, pf[ks]);
;         { const s16x4 lo = vtr(vbase + ks * 1024), hh = vtr(vbase + ks * 1024 + 512); const bf16x8 vf = {lo[0], lo[1], lo[2], lo[3], hh[0], hh[1], hh[2], hh[3]};
;           o0 = __builtin_amdgcn_mfma_f32_32x32x16_bf16(vf, p, o0, 0, 0, 0); }
;         { const s16x4 lo = vtr(vbase + 4096 + ks * 1024), hh = vtr(vbase + 4096 + ks * 1024 + 512); const bf16x8 vf = {lo[0], lo[1], lo[2], lo[3], hh[0], hh[1], hh[2], hh[3]};
;           o1 = __builtin_amdgcn_mfma_f32_32x32x16_bf16(vf, p, o1, 0, 0, 0); }
;     }
; }
; __device__ __forceinline__ void attn_unit(const bf16_t* Qh, const bf16_t* Kh, const bf16_t* Vh, bf16_t* Oh  , int S, int qb, LAS unsigned char* lds, int tid) {
;     ...
;         {
;             f32x16 p0 = {}, p1 = {};
; #pragma unroll
;             for (int s = 0; s < 6; ++s) {
;                 const bf16x8 a0 = *(const LAS bf16x8*)(lds + cur + kfo + s * 32), a1 = *(const LAS bf16x8*)(lds + cur + kfo + 32 * KPITCH + s * 32);
;                 const bf16x8 q = *(const LAS bf16x8*)(ql + (6 + s) * 1024);
;                 p0 = __builtin_amdgcn_mfma_f32_32x32x16_bf16(a0, q, p0, 0, 0, 0); p1 = __builtin_amdgcn_mfma_f32_32x32x16_bf16(a1, q, p1, 0, 0, 0);
	v_mfma_f32_32x32x16_bf16 v[64:79], v[176:179], v[186:189], v[64:79]
	v_mfma_f32_32x32x16_bf16 v[80:95], v[180:183], v[186:189], v[80:95]
	ds_read_b128 v[176:179], v155 offset:96
	ds_read_b128 v[180:183], v155 offset:6752
	ds_read_b128 v[186:189], v135 offset:46080
	v_cvt_pk_bf16_f32 v100, v104, v105
	v_cvt_pk_bf16_f32 v101, v106, v107
	v_exp_f32_e32 v112, v112
	v_exp_f32_e32 v113, v113
	v_exp_f32_e32 v114, v114
	v_exp_f32_e32 v115, v115
	v_add_f32_e32 v141, v141, v108
	v_add_f32_e32 v166, v166, v109
	v_add_f32_e32 v141, v141, v110
	v_add_f32_e32 v166, v166, v111
	s_waitcnt lgkmcnt(3)
	v_mfma_f32_32x32x16_bf16 v[64:79], v[128:131], v[162:165], v[64:79]
	v_mfma_f32_32x32x16_bf16 v[80:95], v[142:145], v[162:165], v[80:95]
	ds_read_b128 v[128:131], v155 offset:128
	ds_read_b128 v[142:145], v155 offset:6784
	ds_read_b128 v[162:165], v135 offset:47104
	v_cvt_pk_bf16_f32 v102, v108, v109
	v_cvt_pk_bf16_f32 v103, v110, v111
	v_exp_f32_e32 v116, v116
	v_exp_f32_e32 v117, v117
	v_exp_f32_e32 v118, v118
	v_exp_f32_e32 v119, v119
	v_add_f32_e32 v141, v141, v112
	v_add_f32_e32 v166, v166, v113
	v_add_f32_e32 v141, v141, v114
	v_add_f32_e32 v166, v166, v115
	s_waitcnt lgkmcnt(3)
	v_mfma_f32_32x32x16_bf16 v[64:79], v[176:179], v[186:189], v[64:79]
	v_mfma_f32_32x32x16_bf16 v[80:95], v[180:183], v[186:189], v[80:95]
	ds_read_b128 v[176:179], v155 offset:160
	ds_read_b128 v[180:183], v155 offset:6816
	ds_read_b128 v[186:189], v135 offset:48128
	v_cvt_pk_bf16_f32 v104, v112, v113
	v_cvt_pk_bf16_f32 v105, v114, v115
	v_exp_f32_e32 v120, v120
	v_exp_f32_e32 v121, v121
	v_exp_f32_e32 v122, v122
	v_exp_f32_e32 v123, v123
	v_add_f32_e32 v141, v141, v116
	v_add_f32_e32 v166, v166, v117
	v_add_f32_e32 v141, v141, v118
	v_add_f32_e32 v166, v166, v119
	s_waitcnt lgkmcnt(3)
	v_mfma_f32_32x32x16_bf16 v[64:79], v[128:131], v[162:165], v[64:79]
	v_mfma_f32_32x32x16_bf16 v[80:95], v[142:145], v[162:165], v[80:95]
	ds_read_b64_tr_b16 v[128:129], v158 offset:34816
	ds_read_b64_tr_b16 v[130:131], v158 offset:35328
	ds_read_b64_tr_b16 v[142:143], v158 offset:38912
	ds_read_b64_tr_b16 v[144:145], v158 offset:39424
	v_cvt_pk_bf16_f32 v106, v116, v117
	v_cvt_pk_bf16_f32 v107, v118, v119
	v_exp_f32_e32 v124, v124
	v_exp_f32_e32 v125, v125
	v_exp_f32_e32 v126, v126
	v_exp_f32_e32 v127, v127
	v_add_f32_e32 v141, v141, v120
	v_add_f32_e32 v166, v166, v121
	v_add_f32_e32 v141, v141, v122
	v_add_f32_e32 v166, v166, v123
	s_waitcnt lgkmcnt(4)
	v_mfma_f32_32x32x16_bf16 v[64:79], v[176:179], v[186:189], v[64:79]
	v_mfma_f32_32x32x16_bf16 v[80:95], v[180:183], v[186:189], v[80:95]
	ds_read_b64_tr_b16 v[176:177], v158 offset:35840
	ds_read_b64_tr_b16 v[178:179], v158 offset:36352
	ds_read_b64_tr_b16 v[180:181], v158 offset:39936
	ds_read_b64_tr_b16 v[182:183], v158 offset:40448
	v_cvt_pk_bf16_f32 v108, v120, v121
	v_cvt_pk_bf16_f32 v109, v122, v123
	v_add_f32_e32 v141, v141, v124
	v_add_f32_e32 v166, v166, v125
	v_add_f32_e32 v141, v141, v126
	v_add_f32_e32 v166, v166, v127
	v_cvt_pk_bf16_f32 v110, v124, v125
	v_cvt_pk_bf16_f32 v111, v126, v127
	v_add_f32_e32 v141, v141, v166
	s_waitcnt lgkmcnt(4)
	v_mfma_f32_32x32x16_bf16 v[48:63], v[128:131], v[96:99], v[48:63]
	v_mfma_f32_32x32x16_bf16 v[32:47], v[142:145], v[96:99], v[32:47]
	ds_read_b64_tr_b16 v[128:129], v158 offset:36864
	ds_read_b64_tr_b16 v[130:131], v158 offset:37376
	ds_read_b64_tr_b16 v[142:143], v158 offset:40960
	ds_read_b64_tr_b16 v[144:145], v158 offset:41472
	v_max3_f32 v248, v64, v65, v66
	v_max3_f32 v249, v80, v81, v82
	v_max3_f32 v248, v248, v67, v68
	v_max3_f32 v249, v249, v83, v84
	v_max3_f32 v248, v248, v69, v70
	v_max3_f32 v249, v249, v85, v86
	v_max3_f32 v248, v248, v71, v72
	v_max3_f32 v249, v249, v87, v88
	v_max3_f32 v248, v248, v73, v74
	v_max3_f32 v249, v249, v89, v90
	s_waitcnt lgkmcnt(4)
	v_mfma_f32_32x32x16_bf16 v[48:63], v[176:179], v[100:103], v[48:63]
	v_mfma_f32_32x32x16_bf16 v[32:47], v[180:183], v[100:103], v[32:47]
	ds_read_b64_tr_b16 v[176:177], v158 offset:37888
	ds_read_b64_tr_b16 v[178:179], v158 offset:38400
	ds_read_b64_tr_b16 v[180:181], v158 offset:41984
	ds_read_b64_tr_b16 v[182:183], v158 offset:42496
	v_max3_f32 v248, v248, v75, v76
	v_max3_f32 v249, v249, v91, v92
	v_max3_f32 v248, v248, v77, v78
	v_max3_f32 v249, v249, v93, v94
	v_max3_f32 v248, v248, v79, v95
	v_max_f32_e32 v248, v248, v249
	v_cmp_lt_f32_e32 vcc, s72, v248
	s_cbranch_vccnz .Lmla_rescAe
; #define LAS __attribute__((address_space(3)))
; __device__ __forceinline__ s16x4 vtr(LAS const unsigned char* p) { return __builtin_bit_cast(s16x4, __builtin_amdgcn_ds_read_tr16_b64_v4i16((LAS s16x4*)p)); }
; __device__ __forceinline__ void softmax_blk(f32x16& p0, f32x16& p1, f32x16& o0, f32x16& o1, float& mhat, float& lrun, u32x4 (&pf)[4], bool first) {
;     ...
;     for (int e = 0; e < 16; ++e) { p0[e] = __builtin_amdgcn_exp2f(p0[e] - mhat); p1[e] = __builtin_amdgcn_exp2f(p1[e] - mhat); s0 += p0[e]; s1 += p1[e]; }
;     lrun += s0 + s1;
;     pf[0] = MLA_PACK(p0, 0); pf[1] = MLA_PACK(p0, 8); pf[2] = MLA_PACK(p1, 0); pf[3] = MLA_PACK(p1, 8);
; }
; __device__ __forceinline__ void pv_blk(const u32x4 (&pf)[4], f32x16& o0, f32x16& o1, LAS const unsigned char* vbase) {
; #pragma unroll
;     for (int ks = 0; ks < 4; ++ks) {
;         const bf16x8 p = __builtin_bit_cast(bf16x8, pf[ks]);
;         { const s16x4 lo = vtr(vbase + ks * 1024), hh = vtr(vbase + ks * 1024 + 512); const bf16x8 vf = {lo[0], lo[1], lo[2], lo[3], hh[0], hh[1], hh[2], hh[3]};
;           o0 = __builtin_amdgcn_mfma_f32_32x32x16_bf16(vf, p, o0, 0, 0, 0); }
;         { const s16x4 lo = vtr(vbase + 4096 + ks * 1024), hh = vtr(vbase + 4096 + ks * 1024 + 512); const bf16x8 vf = {lo[0], lo[1], lo[2], lo[3], hh[0], hh[1], hh[2], hh[3]};
;           o1 = __builtin_amdgcn_mfma_f32_32x32x16_bf16(vf, p, o1, 0, 0, 0); }
;     }
; }
; __device__ __forceinline__ void attn_unit(const bf16_t* Qh, const bf16_t* Kh, const bf16_t* Vh, bf16_t* Oh  , int S, int qb, LAS unsigned char* lds, int tid) {
;     ...
;         {
;             f32x16 p0 = {}, p1 = {};
; #pragma unroll
;             for (int s = 0; s < 6; ++s) {
;                 const bf16x8 a0 = *(const LAS bf16x8*)(lds + cur + kfo + s * 32), a1 = *(const LAS bf16x8*)(lds + cur + kfo + 32 * KPITCH + s * 32);
;                 const bf16x8 q = *(const LAS bf16x8*)(ql + (6 + s) * 1024);
;                 p0 = __builtin_amdgcn_mfma_f32_32x32x16_bf16(a0, q, p0, 0, 0, 0); p1 = __builtin_amdgcn_mfma_f32_32x32x16_bf16(a1, q, p1, 0, 0, 0);
;             }
;             softmax_blk(p0, p1, ob0, ob1, mb, lb, pf, t == 0);
;             pv_blk(pf, ob0, ob1, lds + cur + vb);
;         }
;         *(LAS u32x4*)(lds + nxt + kd0) = ka; *(LAS u32x4*)(lds + (has1 ? nxt : 0u) + kd1) = kb; *(LAS u32x4*)(lds + nxt + vd) = va;
;         __syncthreads();
.Lmla_rescAe_back:
	v_exp_f32_e32 v64, v64
	v_exp_f32_e32 v65, v65
	s_waitcnt lgkmcnt(4)
	v_mfma_f32_32x32x16_bf16 v[48:63], v[128:131], v[104:107], v[48:63]
	v_mfma_f32_32x32x16_bf16 v[32:47], v[142:145], v[104:107], v[32:47]
	ds_read_b128 v[128:131], v155
	ds_read_b128 v[142:145], v155 offset:6656
	ds_read_b128 v[162:165], v135 offset:49152
	v_exp_f32_e32 v66, v66
	v_exp_f32_e32 v67, v67
	v_exp_f32_e32 v68, v68
	v_exp_f32_e32 v69, v69
	v_exp_f32_e32 v70, v70
	v_exp_f32_e32 v71, v71
	v_add_f32_e32 v166, v64, v65
	v_add_f32_e32 v140, v140, v66
	v_add_f32_e32 v166, v166, v67
	v_cvt_pk_bf16_f32 v64, v64, v65
	s_waitcnt lgkmcnt(3)
	v_mfma_f32_32x32x16_bf16 v[48:63], v[176:179], v[108:111], v[48:63]
	v_mfma_f32_32x32x16_bf16 v[32:47], v[180:183], v[108:111], v[32:47]
	ds_read_b128 v[176:179], v155 offset:32
	ds_read_b128 v[180:183], v155 offset:6688
	ds_read_b128 v[186:189], v135 offset:50176
	v_cvt_pk_bf16_f32 v65, v66, v67
	v_exp_f32_e32 v72, v72
	v_exp_f32_e32 v73, v73
	v_exp_f32_e32 v74, v74
	v_exp_f32_e32 v75, v75
	v_add_f32_e32 v140, v140, v68
	v_add_f32_e32 v166, v166, v69
	v_add_f32_e32 v140, v140, v70
	v_add_f32_e32 v166, v166, v71
	v_cvt_pk_bf16_f32 v66, v68, v69
	s_waitcnt lgkmcnt(3)
	v_mfma_f32_32x32x16_bf16 v[96:111], v[128:131], v[162:165], v[190:205]
	v_mfma_f32_32x32x16_bf16 v[112:127], v[142:145], v[162:165], v[190:205]
	ds_read_b128 v[128:131], v155 offset:64
	ds_read_b128 v[142:145], v155 offset:6720
	ds_read_b128 v[162:165], v135 offset:51200
	v_cvt_pk_bf16_f32 v67, v70, v71
	v_exp_f32_e32 v76, v76
	v_exp_f32_e32 v77, v77
	v_exp_f32_e32 v78, v78
	v_exp_f32_e32 v79, v79
	v_add_f32_e32 v140, v140, v72
	v_add_f32_e32 v166, v166, v73
	v_add_f32_e32 v140, v140, v74
	v_add_f32_e32 v166, v166, v75
	s_waitcnt lgkmcnt(3)
	v_mfma_f32_32x32x16_bf16 v[96:111], v[176:179], v[186:189], v[96:111]
	v_mfma_f32_32x32x16_bf16 v[112:127], v[180:183], v[186:189], v[112:127]
	ds_read_b128 v[176:179], v155 offset:96
	ds_read_b128 v[180:183], v155 offset:6752
	ds_read_b128 v[186:189], v135 offset:52224
	v_cvt_pk_bf16_f32 v68, v72, v73
	v_cvt_pk_bf16_f32 v69, v74, v75
	v_exp_f32_e32 v80, v80
	v_exp_f32_e32 v81, v81
	v_exp_f32_e32 v82, v82
	v_exp_f32_e32 v83, v83
	v_add_f32_e32 v140, v140, v76
	v_add_f32_e32 v166, v166, v77
	v_add_f32_e32 v140, v140, v78
	v_add_f32_e32 v166, v166, v79
	s_waitcnt lgkmcnt(3)
	v_mfma_f32_32x32x16_bf16 v[96:111], v[128:131], v[162:165], v[96:111]
	v_mfma_f32_32x32x16_bf16 v[112:127], v[142:145], v[162:165], v[112:127]
	ds_read_b128 v[128:131], v155 offset:128
	ds_read_b128 v[142:145], v155 offset:6784
	ds_read_b128 v[162:165], v135 offset:53248
	v_cvt_pk_bf16_f32 v70, v76, v77
	v_cvt_pk_bf16_f32 v71, v78, v79
	v_exp_f32_e32 v84, v84
	v_exp_f32_e32 v85, v85
	v_exp_f32_e32 v86, v86
	v_exp_f32_e32 v87, v87
	v_add_f32_e32 v140, v140, v80
	v_add_f32_e32 v166, v166, v81
	v_add_f32_e32 v140, v140, v82
	v_add_f32_e32 v166, v166, v83
	s_waitcnt lgkmcnt(3)
	v_mfma_f32_32x32x16_bf16 v[96:111], v[176:179], v[186:189], v[96:111]
	v_mfma_f32_32x32x16_bf16 v[112:127], v[180:183], v[186:189], v[112:127]
	ds_read_b128 v[176:179], v155 offset:160
	ds_read_b128 v[180:183], v155 offset:6816
	ds_read_b128 v[186:189], v135 offset:54272
	v_cvt_pk_bf16_f32 v72, v80, v81
	v_cvt_pk_bf16_f32 v73, v82, v83
	v_exp_f32_e32 v88, v88
	v_exp_f32_e32 v89, v89
	v_exp_f32_e32 v90, v90
	v_exp_f32_e32 v91, v91
	v_add_f32_e32 v140, v140, v84
	v_add_f32_e32 v166, v166, v85
	v_add_f32_e32 v140, v140, v86
	v_add_f32_e32 v166, v166, v87
	s_waitcnt vmcnt(0)
	ds_write_b128 v150, v[218:221] offset:21504
	ds_write_b128 v159, v[222:225]
	ds_write_b128 v157, v[226:229] offset:13312
	s_waitcnt lgkmcnt(6)
	v_mfma_f32_32x32x16_bf16 v[96:111], v[128:131], v[162:165], v[96:111]
	v_mfma_f32_32x32x16_bf16 v[112:127], v[142:145], v[162:165], v[112:127]
	v_cvt_pk_bf16_f32 v74, v84, v85
	v_cvt_pk_bf16_f32 v75, v86, v87
	v_exp_f32_e32 v92, v92
	v_exp_f32_e32 v93, v93
	v_exp_f32_e32 v94, v94
	v_exp_f32_e32 v95, v95
	v_add_f32_e32 v140, v140, v88
	v_add_f32_e32 v166, v166, v89
	v_add_f32_e32 v140, v140, v90
	v_add_f32_e32 v166, v166, v91
	s_waitcnt lgkmcnt(3)
	v_mfma_f32_32x32x16_bf16 v[96:111], v[176:179], v[186:189], v[96:111]
	v_mfma_f32_32x32x16_bf16 v[112:127], v[180:183], v[186:189], v[112:127]
	v_cvt_pk_bf16_f32 v76, v88, v89
	v_cvt_pk_bf16_f32 v77, v90, v91
	v_add_f32_e32 v140, v140, v92
	v_add_f32_e32 v166, v166, v93
	v_add_f32_e32 v140, v140, v94
	v_add_f32_e32 v166, v166, v95
	v_cvt_pk_bf16_f32 v78, v92, v93
	v_cvt_pk_bf16_f32 v79, v94, v95
	v_add_f32_e32 v140, v140, v166
	s_waitcnt lgkmcnt(0)
	s_barrier
	s_add_i32 s1, s1, 1
	s_branch .Lmla_top
.Lmla_epi:
	ds_read_b64_tr_b16 v[128:129], v158 offset:34816
	ds_read_b64_tr_b16 v[130:131], v158 offset:35328
	ds_read_b64_tr_b16 v[142:143], v158 offset:38912
	ds_read_b64_tr_b16 v[144:145], v158 offset:39424
	ds_read_b64_tr_b16 v[176:177], v158 offset:35840
	ds_read_b64_tr_b16 v[178:179], v158 offset:36352
	ds_read_b64_tr_b16 v[180:181], v158 offset:39936
	ds_read_b64_tr_b16 v[182:183], v158 offset:40448
	s_waitcnt lgkmcnt(4)
	v_mfma_f32_32x32x16_bf16 v[16:31], v[128:131], v[64:67], v[16:31]
	v_mfma_f32_32x32x16_bf16 v[0:15], v[142:145], v[64:67], v[0:15]
	ds_read_b64_tr_b16 v[128:129], v158 offset:36864
	ds_read_b64_tr_b16 v[130:131], v158 offset:37376
	ds_read_b64_tr_b16 v[142:143], v158 offset:40960
	ds_read_b64_tr_b16 v[144:145], v158 offset:41472
	v_max3_f32 v248, v96, v97, v98
	v_max3_f32 v249, v112, v113, v114
	v_max3_f32 v248, v248, v99, v100
	v_max3_f32 v249, v249, v115, v116
	v_max3_f32 v248, v248, v101, v102
	v_max3_f32 v249, v249, v117, v118
	v_max3_f32 v248, v248, v103, v104
	v_max3_f32 v249, v249, v119, v120
	v_max3_f32 v248, v248, v105, v106
	v_max3_f32 v249, v249, v121, v122
	v_max3_f32 v248, v248, v107, v108
	v_max3_f32 v249, v249, v123, v124
	v_max3_f32 v248, v248, v109, v110
	v_max3_f32 v249, v249, v125, v126
	v_max3_f32 v248, v248, v111, v127
	v_max_f32_e32 v248, v248, v249
	v_cmp_lt_f32_e32 vcc, s72, v248
	s_cbranch_vccnz .Lmla_rescBe
; #define LAS __attribute__((address_space(3)))
; __device__ __forceinline__ s16x4 vtr(LAS const unsigned char* p) { return __builtin_bit_cast(s16x4, __builtin_amdgcn_ds_read_tr16_b64_v4i16((LAS s16x4*)p)); }
; #define MLA_PACK(P, b) (u32x4){cvt_pk_bf16(P[b], P[b + 1]), cvt_pk_bf16(P[b + 2], P[b + 3]), cvt_pk_bf16(P[b + 4], P[b + 5]), cvt_pk_bf16(P[b + 6], P[b + 7])}
; __device__ __forceinline__ void softmax_blk(f32x16& p0, f32x16& p1, f32x16& o0, f32x16& o1, float& mhat, float& lrun, u32x4 (&pf)[4], bool first) {
;     ...
;     for (int e = 0; e < 16; ++e) { p0[e] = __builtin_amdgcn_exp2f(p0[e] - mhat); p1[e] = __builtin_amdgcn_exp2f(p1[e] - mhat); s0 += p0[e]; s1 += p1[e]; }
;     lrun += s0 + s1;
;     pf[0] = MLA_PACK(p0, 0); pf[1] = MLA_PACK(p0, 8); pf[2] = MLA_PACK(p1, 0); pf[3] = MLA_PACK(p1, 8);
; }
; __device__ __forceinline__ void pv_blk(const u32x4 (&pf)[4], f32x16& o0, f32x16& o1, LAS const unsigned char* vbase) {
; #pragma unroll
;     for (int ks = 0; ks < 4; ++ks) {
;         const bf16x8 p = __builtin_bit_cast(bf16x8, pf[ks]);
;         { const s16x4 lo = vtr(vbase + ks * 1024), hh = vtr(vbase + ks * 1024 + 512); const bf16x8 vf = {lo[0], lo[1], lo[2], lo[3], hh[0], hh[1], hh[2], hh[3]};
;           o0 = __builtin_amdgcn_mfma_f32_32x32x16_bf16(vf, p, o0, 0, 0, 0); }
;         { const s16x4 lo = vtr(vbase + 4096 + ks * 1024), hh = vtr(vbase + 4096 + ks * 1024 + 512); const bf16x8 vf = {lo[0], lo[1], lo[2], lo[3], hh[0], hh[1], hh[2], hh[3]};
;           o1 = __builtin_amdgcn_mfma_f32_32x32x16_bf16(vf, p, o1, 0, 0, 0); }
;     }
; }
; __device__ __forceinline__ void attn_unit(const bf16_t* Qh, const bf16_t* Kh, const bf16_t* Vh, bf16_t* Oh  , int S, int qb, LAS unsigned char* lds, int tid) {
;     ...
;             softmax_blk(p0, p1, ob0, ob1, mb, lb, pf, t == 0);
;             pv_blk(pf, ob0, ob1, lds + cur + vb);
;         }
;         *(LAS u32x4*)(lds + nxt + kd0) = ka; *(LAS u32x4*)(lds + (has1 ? nxt : 0u) + kd1) = kb; *(LAS u32x4*)(lds + nxt + vd) = va;
;         __syncthreads();
;     }
.Lmla_rescBe_back:
	v_exp_f32_e32 v96, v96
	v_exp_f32_e32 v97, v97
	v_exp_f32_e32 v98, v98
	v_exp_f32_e32 v99, v99
	v_exp_f32_e32 v100, v100
	v_exp_f32_e32 v101, v101
	v_exp_f32_e32 v102, v102
	s_waitcnt lgkmcnt(4)
	v_mfma_f32_32x32x16_bf16 v[16:31], v[176:179], v[68:71], v[16:31]
	v_mfma_f32_32x32x16_bf16 v[0:15], v[180:183], v[68:71], v[0:15]
	ds_read_b64_tr_b16 v[176:177], v158 offset:37888
	ds_read_b64_tr_b16 v[178:179], v158 offset:38400
	ds_read_b64_tr_b16 v[180:181], v158 offset:41984
	ds_read_b64_tr_b16 v[182:183], v158 offset:42496
	v_exp_f32_e32 v103, v103
	v_add_f32_e32 v166, v96, v97
	v_add_f32_e32 v141, v141, v98
	v_add_f32_e32 v166, v166, v99
	v_cvt_pk_bf16_f32 v96, v96, v97
	v_cvt_pk_bf16_f32 v97, v98, v99
	v_exp_f32_e32 v104, v104
	v_exp_f32_e32 v105, v105
	v_exp_f32_e32 v106, v106
	v_exp_f32_e32 v107, v107
	v_add_f32_e32 v141, v141, v100
	v_add_f32_e32 v166, v166, v101
	v_add_f32_e32 v141, v141, v102
	v_add_f32_e32 v166, v166, v103
	v_cvt_pk_bf16_f32 v98, v100, v101
	v_cvt_pk_bf16_f32 v99, v102, v103
	v_exp_f32_e32 v108, v108
	v_exp_f32_e32 v109, v109
	v_exp_f32_e32 v110, v110
	v_exp_f32_e32 v111, v111
	v_add_f32_e32 v141, v141, v104
	v_add_f32_e32 v166, v166, v105
	v_add_f32_e32 v141, v141, v106
	v_add_f32_e32 v166, v166, v107
	s_waitcnt lgkmcnt(4)
	v_mfma_f32_32x32x16_bf16 v[16:31], v[128:131], v[72:75], v[16:31]
	v_mfma_f32_32x32x16_bf16 v[0:15], v[142:145], v[72:75], v[0:15]
	ds_read_b64_tr_b16 v[128:129], v158 offset:34816
	ds_read_b64_tr_b16 v[130:131], v158 offset:35328
	ds_read_b64_tr_b16 v[142:143], v158 offset:38912
	ds_read_b64_tr_b16 v[144:145], v158 offset:39424
	v_cvt_pk_bf16_f32 v100, v104, v105
	v_cvt_pk_bf16_f32 v101, v106, v107
	v_exp_f32_e32 v112, v112
	v_exp_f32_e32 v113, v113
	v_exp_f32_e32 v114, v114
	v_exp_f32_e32 v115, v115
	v_add_f32_e32 v141, v141, v108
	v_add_f32_e32 v166, v166, v109
	v_add_f32_e32 v141, v141, v110
	v_add_f32_e32 v166, v166, v111
	v_cvt_pk_bf16_f32 v102, v108, v109
	v_cvt_pk_bf16_f32 v103, v110, v111
	v_exp_f32_e32 v116, v116
	v_exp_f32_e32 v117, v117
	v_exp_f32_e32 v118, v118
	v_exp_f32_e32 v119, v119
	v_add_f32_e32 v141, v141, v112
	v_add_f32_e32 v166, v166, v113
	v_add_f32_e32 v141, v141, v114
	v_add_f32_e32 v166, v166, v115
	v_cvt_pk_bf16_f32 v104, v112, v113
	v_cvt_pk_bf16_f32 v105, v114, v115
	v_exp_f32_e32 v120, v120
	v_exp_f32_e32 v121, v121
	v_exp_f32_e32 v122, v122
	s_waitcnt lgkmcnt(4)
	v_mfma_f32_32x32x16_bf16 v[16:31], v[176:179], v[76:79], v[16:31]
	v_mfma_f32_32x32x16_bf16 v[0:15], v[180:183], v[76:79], v[0:15]
	ds_read_b64_tr_b16 v[176:177], v158 offset:35840
	ds_read_b64_tr_b16 v[178:179], v158 offset:36352
	ds_read_b64_tr_b16 v[180:181], v158 offset:39936
	ds_read_b64_tr_b16 v[182:183], v158 offset:40448
	v_exp_f32_e32 v123, v123
	v_add_f32_e32 v141, v141, v116
	v_add_f32_e32 v166, v166, v117
	v_add_f32_e32 v141, v141, v118
	v_add_f32_e32 v166, v166, v119
	v_cvt_pk_bf16_f32 v106, v116, v117
	v_cvt_pk_bf16_f32 v107, v118, v119
	v_exp_f32_e32 v124, v124
	v_exp_f32_e32 v125, v125
	v_exp_f32_e32 v126, v126
	v_exp_f32_e32 v127, v127
	v_add_f32_e32 v141, v141, v120
	v_add_f32_e32 v166, v166, v121
	v_add_f32_e32 v141, v141, v122
	v_add_f32_e32 v166, v166, v123
	v_cvt_pk_bf16_f32 v108, v120, v121
	v_cvt_pk_bf16_f32 v109, v122, v123
	v_add_f32_e32 v141, v141, v124
	v_add_f32_e32 v166, v166, v125
	v_add_f32_e32 v141, v141, v126
	v_add_f32_e32 v166, v166, v127
	v_cvt_pk_bf16_f32 v110, v124, v125
	v_cvt_pk_bf16_f32 v111, v126, v127
	v_add_f32_e32 v141, v141, v166
	s_waitcnt lgkmcnt(4)
	v_mfma_f32_32x32x16_bf16 v[48:63], v[128:131], v[96:99], v[48:63]
	v_mfma_f32_32x32x16_bf16 v[32:47], v[142:145], v[96:99], v[32:47]
	ds_read_b64_tr_b16 v[128:129], v158 offset:36864
	ds_read_b64_tr_b16 v[130:131], v158 offset:37376
	ds_read_b64_tr_b16 v[142:143], v158 offset:40960
	ds_read_b64_tr_b16 v[144:145], v158 offset:41472
	s_waitcnt lgkmcnt(4)
	v_mfma_f32_32x32x16_bf16 v[48:63], v[176:179], v[100:103], v[48:63]
	v_mfma_f32_32x32x16_bf16 v[32:47], v[180:183], v[100:103], v[32:47]
	ds_read_b64_tr_b16 v[176:177], v158 offset:37888
	ds_read_b64_tr_b16 v[178:179], v158 offset:38400
	ds_read_b64_tr_b16 v[180:181], v158 offset:41984
	ds_read_b64_tr_b16 v[182:183], v158 offset:42496
	s_waitcnt lgkmcnt(4)
	v_mfma_f32_32x32x16_bf16 v[48:63], v[128:131], v[104:107], v[48:63]
	v_mfma_f32_32x32x16_bf16 v[32:47], v[142:145], v[104:107], v[32:47]
	s_waitcnt lgkmcnt(0)
	v_mfma_f32_32x32x16_bf16 v[48:63], v[176:179], v[108:111], v[48:63]
	v_mfma_f32_32x32x16_bf16 v[32:47], v[180:183], v[108:111], v[32:47]
	s_waitcnt lgkmcnt(0)
	s_barrier
	s_setprio 0
	s_nop 7
	s_nop 3
	s_branch .LBB0_75
; __device__ __forceinline__ void softmax_blk(f32x16& p0, f32x16& p1, f32x16& o0, f32x16& o1, float& mhat, float& lrun, u32x4 (&pf)[4], bool first) {
;     ...
;     if (first || __any(rm - mhat > THR)) {
;         const float mn = first ? rm : fmaxf(rm, mhat); const float f = first ? 0.f : __builtin_amdgcn_exp2f(mhat - mn); mhat = mn; lrun *= f;
; #pragma unroll
;         for (int e = 0; e < 16; ++e) { o0[e] *= f; o1[e] *= f; }
;     }
.Lmla_rescAp:
	v_mov_b32_e32 v251, v248
	s_nop 1
	v_permlane32_swap_b32_e32 v248, v251
	v_max_f32_e32 v167, v248, v251
	v_max_f32_e32 v249, 0, v167
	v_exp_f32_e64 v250, -v249
	s_nop 0
	v_mul_f32_e32 v140, v140, v250
	v_pk_mul_f32 v[0:1], v[0:1], v[250:251] op_sel_hi:[1,0]
	v_pk_mul_f32 v[2:3], v[2:3], v[250:251] op_sel_hi:[1,0]
	v_pk_mul_f32 v[4:5], v[4:5], v[250:251] op_sel_hi:[1,0]
	v_pk_mul_f32 v[6:7], v[6:7], v[250:251] op_sel_hi:[1,0]
	v_pk_mul_f32 v[8:9], v[8:9], v[250:251] op_sel_hi:[1,0]
	v_pk_mul_f32 v[10:11], v[10:11], v[250:251] op_sel_hi:[1,0]
	v_pk_mul_f32 v[12:13], v[12:13], v[250:251] op_sel_hi:[1,0]
	v_pk_mul_f32 v[14:15], v[14:15], v[250:251] op_sel_hi:[1,0]
	v_pk_mul_f32 v[16:17], v[16:17], v[250:251] op_sel_hi:[1,0]
	v_pk_mul_f32 v[18:19], v[18:19], v[250:251] op_sel_hi:[1,0]
	v_pk_mul_f32 v[20:21], v[20:21], v[250:251] op_sel_hi:[1,0]
	v_pk_mul_f32 v[22:23], v[22:23], v[250:251] op_sel_hi:[1,0]
	v_pk_mul_f32 v[24:25], v[24:25], v[250:251] op_sel_hi:[1,0]
	v_pk_mul_f32 v[26:27], v[26:27], v[250:251] op_sel_hi:[1,0]
	v_pk_mul_f32 v[28:29], v[28:29], v[250:251] op_sel_hi:[1,0]
	v_pk_mul_f32 v[30:31], v[30:31], v[250:251] op_sel_hi:[1,0]
	v_sub_f32_e32 v64, v64, v249
	v_sub_f32_e32 v65, v65, v249
	v_sub_f32_e32 v66, v66, v249
	v_sub_f32_e32 v67, v67, v249
	v_sub_f32_e32 v68, v68, v249
	v_sub_f32_e32 v69, v69, v249
	v_sub_f32_e32 v70, v70, v249
	v_sub_f32_e32 v71, v71, v249
	v_sub_f32_e32 v72, v72, v249
	v_sub_f32_e32 v73, v73, v249
	v_sub_f32_e32 v74, v74, v249
	v_sub_f32_e32 v75, v75, v249
	v_sub_f32_e32 v76, v76, v249
	v_sub_f32_e32 v77, v77, v249
	v_sub_f32_e32 v78, v78, v249
	v_sub_f32_e32 v79, v79, v249
	v_sub_f32_e32 v80, v80, v249
	v_sub_f32_e32 v81, v81, v249
	v_sub_f32_e32 v82, v82, v249
	v_sub_f32_e32 v83, v83, v249
	v_sub_f32_e32 v84, v84, v249
	v_sub_f32_e32 v85, v85, v249
	v_sub_f32_e32 v86, v86, v249
	v_sub_f32_e32 v87, v87, v249
	v_sub_f32_e32 v88, v88, v249
	v_sub_f32_e32 v89, v89, v249
	v_sub_f32_e32 v90, v90, v249
	v_sub_f32_e32 v91, v91, v249
	v_sub_f32_e32 v92, v92, v249
	v_sub_f32_e32 v93, v93, v249
	v_sub_f32_e32 v94, v94, v249
	v_sub_f32_e32 v95, v95, v249
	v_sub_f32_e32 v232, v232, v249
	v_sub_f32_e32 v233, v233, v249
	v_sub_f32_e32 v234, v234, v249
	v_sub_f32_e32 v235, v235, v249
	v_sub_f32_e32 v236, v236, v249
	v_sub_f32_e32 v237, v237, v249
	v_sub_f32_e32 v238, v238, v249
	v_sub_f32_e32 v239, v239, v249
	v_sub_f32_e32 v240, v240, v249
	v_sub_f32_e32 v241, v241, v249
	v_sub_f32_e32 v242, v242, v249
	v_sub_f32_e32 v243, v243, v249
	v_sub_f32_e32 v244, v244, v249
	v_sub_f32_e32 v245, v245, v249
	v_sub_f32_e32 v246, v246, v249
	v_sub_f32_e32 v247, v247, v249
	s_branch .Lmla_rescAp_back

; __device__ __forceinline__ void softmax_blk(f32x16& p0, f32x16& p1, f32x16& o0, f32x16& o1, float& mhat, float& lrun, u32x4 (&pf)[4], bool first) {
;     ...
;     if (first || __any(rm - mhat > THR)) {
;         const float mn = first ? rm : fmaxf(rm, mhat); const float f = first ? 0.f : __builtin_amdgcn_exp2f(mhat - mn); mhat = mn; lrun *= f;
; #pragma unroll
;         for (int e = 0; e < 16; ++e) { o0[e] *= f; o1[e] *= f; }
;     }
.Lmla_rescBo:
	v_mov_b32_e32 v251, v248
	s_nop 1
	v_permlane32_swap_b32_e32 v248, v251
	v_max_f32_e32 v167, v248, v251
	v_max_f32_e32 v249, 0, v167
	v_exp_f32_e64 v250, -v249
	s_nop 0
	v_mul_f32_e32 v141, v141, v250
	v_pk_mul_f32 v[32:33], v[32:33], v[250:251] op_sel_hi:[1,0]
	v_pk_mul_f32 v[34:35], v[34:35], v[250:251] op_sel_hi:[1,0]
	v_pk_mul_f32 v[36:37], v[36:37], v[250:251] op_sel_hi:[1,0]
	v_pk_mul_f32 v[38:39], v[38:39], v[250:251] op_sel_hi:[1,0]
	v_pk_mul_f32 v[40:41], v[40:41], v[250:251] op_sel_hi:[1,0]
	v_pk_mul_f32 v[42:43], v[42:43], v[250:251] op_sel_hi:[1,0]
	v_pk_mul_f32 v[44:45], v[44:45], v[250:251] op_sel_hi:[1,0]
	v_pk_mul_f32 v[46:47], v[46:47], v[250:251] op_sel_hi:[1,0]
	v_pk_mul_f32 v[48:49], v[48:49], v[250:251] op_sel_hi:[1,0]
	v_pk_mul_f32 v[50:51], v[50:51], v[250:251] op_sel_hi:[1,0]
	v_pk_mul_f32 v[52:53], v[52:53], v[250:251] op_sel_hi:[1,0]
	v_pk_mul_f32 v[54:55], v[54:55], v[250:251] op_sel_hi:[1,0]
	v_pk_mul_f32 v[56:57], v[56:57], v[250:251] op_sel_hi:[1,0]
	v_pk_mul_f32 v[58:59], v[58:59], v[250:251] op_sel_hi:[1,0]
	v_pk_mul_f32 v[60:61], v[60:61], v[250:251] op_sel_hi:[1,0]
	v_pk_mul_f32 v[62:63], v[62:63], v[250:251] op_sel_hi:[1,0]
	v_sub_f32_e32 v96, v96, v249
	v_sub_f32_e32 v97, v97, v249
	v_sub_f32_e32 v98, v98, v249
	v_sub_f32_e32 v99, v99, v249
	v_sub_f32_e32 v100, v100, v249
	v_sub_f32_e32 v101, v101, v249
	v_sub_f32_e32 v102, v102, v249
	v_sub_f32_e32 v103, v103, v249
	v_sub_f32_e32 v104, v104, v249
	v_sub_f32_e32 v105, v105, v249
	v_sub_f32_e32 v106, v106, v249
	v_sub_f32_e32 v107, v107, v249
	v_sub_f32_e32 v108, v108, v249
	v_sub_f32_e32 v109, v109, v249
	v_sub_f32_e32 v110, v110, v249
	v_sub_f32_e32 v111, v111, v249
	v_sub_f32_e32 v112, v112, v249
	v_sub_f32_e32 v113, v113, v249
	v_sub_f32_e32 v114, v114, v249
	v_sub_f32_e32 v115, v115, v249
	v_sub_f32_e32 v116, v116, v249
	v_sub_f32_e32 v117, v117, v249
	v_sub_f32_e32 v118, v118, v249
	v_sub_f32_e32 v119, v119, v249
	v_sub_f32_e32 v120, v120, v249
	v_sub_f32_e32 v121, v121, v249
	v_sub_f32_e32 v122, v122, v249
	v_sub_f32_e32 v123, v123, v249
	v_sub_f32_e32 v124, v124, v249
	v_sub_f32_e32 v125, v125, v249
	v_sub_f32_e32 v126, v126, v249
	v_sub_f32_e32 v127, v127, v249
	v_sub_f32_e32 v190, v190, v249
	v_sub_f32_e32 v191, v191, v249
	v_sub_f32_e32 v192, v192, v249
	v_sub_f32_e32 v193, v193, v249
	v_sub_f32_e32 v194, v194, v249
	v_sub_f32_e32 v195, v195, v249
	v_sub_f32_e32 v196, v196, v249
	v_sub_f32_e32 v197, v197, v249
	v_sub_f32_e32 v198, v198, v249
	v_sub_f32_e32 v199, v199, v249
	v_sub_f32_e32 v200, v200, v249
	v_sub_f32_e32 v201, v201, v249
	v_sub_f32_e32 v202, v202, v249
	v_sub_f32_e32 v203, v203, v249
	v_sub_f32_e32 v204, v204, v249
	v_sub_f32_e32 v205, v205, v249
	s_branch .Lmla_rescBo_back
